# hand-written kind-specialised in-proj epilogue (rope via ds_swizzle, prefetched rope table, scalar-based saddr stores) on top of v23
# speedup vs baseline: 1.0220x; 1.0088x over previous
;     __device__ __forceinline__ void operator()(const f32x4 (&acc)[2][2][4][2], const Unit& u, int wr, int wc, int fr, int fq, PG8_LAS float* stash, int par, PG8_LAS unsigned char* stg, const Unit& un) const {
;     ...
;                 const int row = u.pm * BM + ai * HALF + wr * 64 + m * 16 + fr, pos = row & 4095, b = row >> 12;
;                 const float rs = rsa[ai][m];
; #pragma unroll
;                 for (int bj = 0; bj < 2; ++bj) {
;                     int kind;
;                     if (odd) kind = (u.pn < 6) ? 0 : (u.pn == 6 ? 1 : 2);
;                     else     kind = (u.pn < 2) ? 0 : (u.pn == 2 ? (wc < 2 ? 1 : 2) : 3);
;                     float v[8];
; #pragma unroll
;                     for (int i = 0; i < 4; ++i) { v[i] = acc[ai][bj][m][0][i] * rs; v[4 + i] = acc[ai][bj][m][1][i] * rs; }
;                     if (kind <= 1 && bj == 0) {
;                         const f32x4 c0 = *(const f32x4*)(cs + pos * 16), c1 = *(const f32x4*)(cs + pos * 16 + 4), s0 = *(const f32x4*)(cs + pos * 16 + 8), s1 = *(const f32x4*)(cs + pos * 16 + 12);
; #pragma unroll
;                         for (int i = 0; i < 8; ++i) {
;                             const float c = i < 4 ? c0[i & 3] : c1[i & 3], s = i < 4 ? s0[i & 3] : s1[i & 3];
;                             const float pr = peer_x16(v[i], fq);
;                             const float r = (fq == 0) ? (v[i] * c - pr * s) : (v[i] * c + pr * s);
;                             v[i] = (fq < 2) ? r : v[i];
;                         }
;                     }
;                     if (kind == 0) {
; #pragma unroll
;                         for (int i = 0; i < 8; ++i) v[i] *= C2Q;
;                     }
;                     { u32x4 w; w.x = cvt_pk_bf16(v[0], v[1]); w.y = cvt_pk_bf16(v[2], v[3]); w.z = cvt_pk_bf16(v[4], v[5]); w.w = cvt_pk_bf16(v[6], v[7]);
;                       *(PG8_LAS u32x4*)(stg + fr * 144 + fq * 16 + bj * 64) = w; }
;                 }
;                 {
;                     int kind;
;                     if (odd) kind = (u.pn < 6) ? 0 : (u.pn == 6 ? 1 : 2);
;                     else     kind = (u.pn < 2) ? 0 : (u.pn == 2 ? (wc < 2 ? 1 : 2) : 3);
; #pragma unroll
;                     for (int i = 0; i < 2; ++i) { const int c = fq * 16 + fr + 64 * i, rr = c >> 3, pc = c & 7;
;                         const u32x4 w = *(const PG8_LAS u32x4*)(stg + rr * 144 + pc * 16);
.LBB0_145:
	s_waitcnt lgkmcnt(0)
	s_lshl_b32 s19, s56, 8
	s_add_i32 s19, s19, s51
	v_mov_b32_e32 v201, 0x80000000
	s_nop 0
	v_cndmask_b32_e64 v201, 0, v201, s[34:35]
	s_cmp_eq_u32 s53, 1
	s_cbranch_scc1 .Lipe_kv
	s_cmp_eq_u32 s53, 2
	s_cbranch_scc1 .Lipe_kv
	s_lshl_b32 s65, s48, 1
	s_mul_i32 s44, s19, s65
	s_add_u32 s98, s78, s44
	s_addc_u32 s99, s79, 0
	s_lshl_b32 s44, s18, 9
	s_add_u32 s98, s98, s44
	s_addc_u32 s99, s99, 0
	s_lshl_b32 s44, s10, 7
	s_add_u32 s98, s98, s44
	s_addc_u32 s99, s99, 0
	s_mov_b32 s66, s65
	s_lshl_b32 s67, s65, 3
	v_mul_u32_u24_e32 v200, s65, v173
	v_lshl_add_u32 v200, v140, 1, v200
	s_branch .Lipe_dispatch
.Lipe_kv:
	s_cmp_eq_u32 s53, 1
	s_cselect_b32 s98, s26, s31
	s_cselect_b32 s99, s27, s33
	s_lshr_b32 s44, s19, 12
	s_and_b32 s45, s19, 0xfff
	s_and_b64 vcc, exec, s[46:47]
	s_cbranch_vccz .Lipe_kv_even
	s_lshl_b32 s44, s44, 2
	s_or_b32 s44, s44, s10
	s_lshl_b32 s44, s44, 19
	s_lshr_b32 s45, s45, 4
	s_lshl_b32 s45, s45, 7
	s_mov_b32 s66, 8
	s_mov_b32 s67, 0x40000
	v_lshlrev_b32_e32 v200, 15, v173
	s_branch .Lipe_kv_join
.Lipe_kv_even:
	s_lshl_b32 s44, s44, 1
	s_or_b32 s44, s44, s16
	s_lshl_b32 s44, s44, 19
	s_lshl_b32 s45, s45, 7
	s_movk_i32 s66, 0x80
	s_movk_i32 s67, 0x400
	v_lshlrev_b32_e32 v200, 7, v173
.Lipe_kv_join:
	s_add_u32 s98, s98, s44
	s_addc_u32 s99, s99, 0
	s_add_u32 s98, s98, s45
	s_addc_u32 s99, s99, 0
	v_lshl_add_u32 v200, v140, 1, v200
.Lipe_dispatch:
	s_cmp_eq_u32 s53, 0
	s_cbranch_scc1 .Lipe_Q
	s_cmp_eq_u32 s53, 1
	s_cbranch_scc1 .Lipe_K
	s_branch .Lipe_P
.Lipe_Q:
	s_add_i32 s44, s19, 0
	s_and_b32 s44, s44, 0xfff
	v_or_b32_e32 v0, s44, v141
	v_lshlrev_b32_e32 v0, 6, v0
	global_load_dwordx4 v[154:157], v0, s[62:63]
	global_load_dwordx4 v[158:161], v0, s[62:63] offset:16
	global_load_dwordx4 v[162:165], v0, s[62:63] offset:32
	global_load_dwordx4 v[166:169], v0, s[62:63] offset:48
	s_add_i32 s44, s19, 16
	s_and_b32 s44, s44, 0xfff
	v_or_b32_e32 v0, s44, v141
	v_lshlrev_b32_e32 v0, 6, v0
	global_load_dwordx4 v[218:221], v0, s[62:63]
	global_load_dwordx4 v[222:225], v0, s[62:63] offset:16
	global_load_dwordx4 v[226:229], v0, s[62:63] offset:32
	global_load_dwordx4 v[230:233], v0, s[62:63] offset:48
	v_pk_mul_f32 v[118:119], v[118:119], v[152:153] op_sel_hi:[1,0]
	v_pk_mul_f32 v[120:121], v[120:121], v[152:153] op_sel_hi:[1,0]
	v_pk_mul_f32 v[114:115], v[114:115], v[152:153] op_sel_hi:[1,0]
	v_pk_mul_f32 v[116:117], v[116:117], v[152:153] op_sel_hi:[1,0]
	v_pk_mul_f32 v[118:119], v[118:119], s[30:31] op_sel_hi:[1,0]
	v_pk_mul_f32 v[120:121], v[120:121], s[30:31] op_sel_hi:[1,0]
	v_pk_mul_f32 v[114:115], v[114:115], s[30:31] op_sel_hi:[1,0]
	v_pk_mul_f32 v[116:117], v[116:117], s[30:31] op_sel_hi:[1,0]
	v_cvt_pk_bf16_f32 v118, v118, v119
	v_cvt_pk_bf16_f32 v119, v120, v121
	v_cvt_pk_bf16_f32 v120, v114, v115
	v_cvt_pk_bf16_f32 v121, v116, v117
	v_pk_mul_f32 v[126:127], v[126:127], v[152:153] op_sel_hi:[1,0]
	v_pk_mul_f32 v[128:129], v[128:129], v[152:153] op_sel_hi:[1,0]
	v_pk_mul_f32 v[122:123], v[122:123], v[152:153] op_sel_hi:[1,0]
	v_pk_mul_f32 v[124:125], v[124:125], v[152:153] op_sel_hi:[1,0]
	ds_swizzle_b32 v114, v126 offset:0x401f
	ds_swizzle_b32 v115, v127 offset:0x401f
	ds_swizzle_b32 v116, v128 offset:0x401f
	ds_swizzle_b32 v117, v129 offset:0x401f
	s_waitcnt vmcnt(4)
	v_xor_b32_e32 v162, v201, v162
	v_xor_b32_e32 v163, v201, v163
	v_xor_b32_e32 v164, v201, v164
	v_xor_b32_e32 v165, v201, v165
	v_xor_b32_e32 v166, v201, v166
	v_xor_b32_e32 v167, v201, v167
	v_xor_b32_e32 v168, v201, v168
	v_xor_b32_e32 v169, v201, v169
	s_waitcnt lgkmcnt(0)
	v_mul_f32_e32 v114, v162, v114
	v_fmac_f32_e32 v114, v126, v154
	v_cndmask_b32_e64 v126, v126, v114, s[38:39]
	v_mul_f32_e32 v115, v163, v115
	v_fmac_f32_e32 v115, v127, v155
	v_cndmask_b32_e64 v127, v127, v115, s[38:39]
	v_mul_f32_e32 v116, v164, v116
	v_fmac_f32_e32 v116, v128, v156
	v_cndmask_b32_e64 v128, v128, v116, s[38:39]
	v_mul_f32_e32 v117, v165, v117
	v_fmac_f32_e32 v117, v129, v157
	v_cndmask_b32_e64 v129, v129, v117, s[38:39]
	ds_swizzle_b32 v114, v122 offset:0x401f
	ds_swizzle_b32 v115, v123 offset:0x401f
	ds_swizzle_b32 v116, v124 offset:0x401f
	ds_swizzle_b32 v117, v125 offset:0x401f
	s_waitcnt lgkmcnt(0)
	v_mul_f32_e32 v114, v166, v114
	v_fmac_f32_e32 v114, v122, v158
	v_cndmask_b32_e64 v122, v122, v114, s[38:39]
	v_mul_f32_e32 v115, v167, v115
	v_fmac_f32_e32 v115, v123, v159
	v_cndmask_b32_e64 v123, v123, v115, s[38:39]
	v_mul_f32_e32 v116, v168, v116
	v_fmac_f32_e32 v116, v124, v160
	v_cndmask_b32_e64 v124, v124, v116, s[38:39]
	v_mul_f32_e32 v117, v169, v117
	v_fmac_f32_e32 v117, v125, v161
	v_cndmask_b32_e64 v125, v125, v117, s[38:39]
	v_pk_mul_f32 v[126:127], v[126:127], s[30:31] op_sel_hi:[1,0]
	v_pk_mul_f32 v[128:129], v[128:129], s[30:31] op_sel_hi:[1,0]
	v_pk_mul_f32 v[122:123], v[122:123], s[30:31] op_sel_hi:[1,0]
	v_pk_mul_f32 v[124:125], v[124:125], s[30:31] op_sel_hi:[1,0]
	v_cvt_pk_bf16_f32 v126, v126, v127
	v_cvt_pk_bf16_f32 v127, v128, v129
	v_cvt_pk_bf16_f32 v128, v122, v123
	v_cvt_pk_bf16_f32 v129, v124, v125
	ds_write_b128 v178, v[126:129]
	ds_write_b128 v178, v[118:121] offset:64
	ds_read_b128 v[122:125], v180
	ds_read_b128 v[114:117], v180 offset:1152
	s_add_i32 s44, s19, 32
	s_and_b32 s44, s44, 0xfff
	v_or_b32_e32 v0, s44, v141
	v_lshlrev_b32_e32 v0, 6, v0
	global_load_dwordx4 v[154:157], v0, s[62:63]
	global_load_dwordx4 v[158:161], v0, s[62:63] offset:16
	global_load_dwordx4 v[162:165], v0, s[62:63] offset:32
	global_load_dwordx4 v[166:169], v0, s[62:63] offset:48
	v_pk_mul_f32 v[102:103], v[102:103], v[152:153] op_sel:[0,1]
	v_pk_mul_f32 v[104:105], v[104:105], v[152:153] op_sel:[0,1]
	v_pk_mul_f32 v[98:99], v[98:99], v[152:153] op_sel:[0,1]
	v_pk_mul_f32 v[100:101], v[100:101], v[152:153] op_sel:[0,1]
	v_pk_mul_f32 v[102:103], v[102:103], s[30:31] op_sel_hi:[1,0]
	v_pk_mul_f32 v[104:105], v[104:105], s[30:31] op_sel_hi:[1,0]
	v_pk_mul_f32 v[98:99], v[98:99], s[30:31] op_sel_hi:[1,0]
	v_pk_mul_f32 v[100:101], v[100:101], s[30:31] op_sel_hi:[1,0]
	v_cvt_pk_bf16_f32 v102, v102, v103
	v_cvt_pk_bf16_f32 v103, v104, v105
	v_cvt_pk_bf16_f32 v104, v98, v99
	v_cvt_pk_bf16_f32 v105, v100, v101
	v_pk_mul_f32 v[110:111], v[110:111], v[152:153] op_sel:[0,1]
	v_pk_mul_f32 v[112:113], v[112:113], v[152:153] op_sel:[0,1]
	v_pk_mul_f32 v[106:107], v[106:107], v[152:153] op_sel:[0,1]
	v_pk_mul_f32 v[108:109], v[108:109], v[152:153] op_sel:[0,1]
	ds_swizzle_b32 v98, v110 offset:0x401f
	ds_swizzle_b32 v99, v111 offset:0x401f
	ds_swizzle_b32 v100, v112 offset:0x401f
	ds_swizzle_b32 v101, v113 offset:0x401f
	s_waitcnt vmcnt(4)
;     __device__ __forceinline__ void operator()(const f32x4 (&acc)[2][2][4][2], const Unit& u, int wr, int wc, int fr, int fq, PG8_LAS float* stash, int par, PG8_LAS unsigned char* stg, const Unit& un) const {
;     ...
;                     for (int i = 0; i < 4; ++i) { v[i] = acc[ai][bj][m][0][i] * rs; v[4 + i] = acc[ai][bj][m][1][i] * rs; }
;                     if (kind <= 1 && bj == 0) {
;                         const f32x4 c0 = *(const f32x4*)(cs + pos * 16), c1 = *(const f32x4*)(cs + pos * 16 + 4), s0 = *(const f32x4*)(cs + pos * 16 + 8), s1 = *(const f32x4*)(cs + pos * 16 + 12);
; #pragma unroll
;                         for (int i = 0; i < 8; ++i) {
;                             const float c = i < 4 ? c0[i & 3] : c1[i & 3], s = i < 4 ? s0[i & 3] : s1[i & 3];
;                             const float pr = peer_x16(v[i], fq);
;                             const float r = (fq == 0) ? (v[i] * c - pr * s) : (v[i] * c + pr * s);
;                             v[i] = (fq < 2) ? r : v[i];
;                         }
;                     }
;                     if (kind == 0) {
; #pragma unroll
;                         for (int i = 0; i < 8; ++i) v[i] *= C2Q;
;                     }
;                     { u32x4 w; w.x = cvt_pk_bf16(v[0], v[1]); w.y = cvt_pk_bf16(v[2], v[3]); w.z = cvt_pk_bf16(v[4], v[5]); w.w = cvt_pk_bf16(v[6], v[7]);
;                       *(PG8_LAS u32x4*)(stg + fr * 144 + fq * 16 + bj * 64) = w; }
;                 }
;                 {
;                     int kind;
;                     if (odd) kind = (u.pn < 6) ? 0 : (u.pn == 6 ? 1 : 2);
;                     else     kind = (u.pn < 2) ? 0 : (u.pn == 2 ? (wc < 2 ? 1 : 2) : 3);
; #pragma unroll
;                     for (int i = 0; i < 2; ++i) { const int c = fq * 16 + fr + 64 * i, rr = c >> 3, pc = c & 7;
;                         const u32x4 w = *(const PG8_LAS u32x4*)(stg + rr * 144 + pc * 16);
;                         const int rowc = row - fr + rr, posc = rowc & 4095;
;                         if (kind == 1 || kind == 2) {
;                             bf16_t* dst = (kind == 1) ? kd : vt;
;                             if (odd) *(u32x4*)(dst + (size_t)(b * 4 + wc) * (4096 * 64) + (size_t)((posc & 15) * 256 + (posc >> 4)) * 64 + pc * 8) = w;
;                             else     *(u32x4*)(dst + (size_t)(b * 2 + (wc & 1)) * (4096 * 64) + (size_t)posc * 64 + pc * 8) = w;
	v_xor_b32_e32 v226, v201, v226
	v_xor_b32_e32 v227, v201, v227
	v_xor_b32_e32 v228, v201, v228
	v_xor_b32_e32 v229, v201, v229
	v_xor_b32_e32 v230, v201, v230
	v_xor_b32_e32 v231, v201, v231
	v_xor_b32_e32 v232, v201, v232
	v_xor_b32_e32 v233, v201, v233
	s_waitcnt lgkmcnt(0)
	v_mul_f32_e32 v98, v226, v98
	v_fmac_f32_e32 v98, v110, v218
	v_cndmask_b32_e64 v110, v110, v98, s[38:39]
	v_mul_f32_e32 v99, v227, v99
	v_fmac_f32_e32 v99, v111, v219
	v_cndmask_b32_e64 v111, v111, v99, s[38:39]
	v_mul_f32_e32 v100, v228, v100
	v_fmac_f32_e32 v100, v112, v220
	v_cndmask_b32_e64 v112, v112, v100, s[38:39]
	v_mul_f32_e32 v101, v229, v101
	v_fmac_f32_e32 v101, v113, v221
	v_cndmask_b32_e64 v113, v113, v101, s[38:39]
	ds_swizzle_b32 v98, v106 offset:0x401f
	ds_swizzle_b32 v99, v107 offset:0x401f
	ds_swizzle_b32 v100, v108 offset:0x401f
	ds_swizzle_b32 v101, v109 offset:0x401f
	s_waitcnt lgkmcnt(0)
	v_mul_f32_e32 v98, v230, v98
	v_fmac_f32_e32 v98, v106, v222
	v_cndmask_b32_e64 v106, v106, v98, s[38:39]
	v_mul_f32_e32 v99, v231, v99
	v_fmac_f32_e32 v99, v107, v223
	v_cndmask_b32_e64 v107, v107, v99, s[38:39]
	v_mul_f32_e32 v100, v232, v100
	v_fmac_f32_e32 v100, v108, v224
	v_cndmask_b32_e64 v108, v108, v100, s[38:39]
	v_mul_f32_e32 v101, v233, v101
	v_fmac_f32_e32 v101, v109, v225
	v_cndmask_b32_e64 v109, v109, v101, s[38:39]
	v_pk_mul_f32 v[110:111], v[110:111], s[30:31] op_sel_hi:[1,0]
	v_pk_mul_f32 v[112:113], v[112:113], s[30:31] op_sel_hi:[1,0]
	v_pk_mul_f32 v[106:107], v[106:107], s[30:31] op_sel_hi:[1,0]
	v_pk_mul_f32 v[108:109], v[108:109], s[30:31] op_sel_hi:[1,0]
	v_cvt_pk_bf16_f32 v110, v110, v111
	v_cvt_pk_bf16_f32 v111, v112, v113
	v_cvt_pk_bf16_f32 v112, v106, v107
	v_cvt_pk_bf16_f32 v113, v108, v109
	s_mov_b32 s100, s98
	s_mov_b32 s101, s99
	global_store_dwordx4 v200, v[122:125], s[100:101] nt
	s_add_u32 s100, s100, s67
	s_addc_u32 s101, s101, 0
	global_store_dwordx4 v200, v[114:117], s[100:101] nt
	ds_write_b128 v178, v[110:113]
	ds_write_b128 v178, v[102:105] offset:64
	ds_read_b128 v[106:109], v180
	ds_read_b128 v[98:101], v180 offset:1152
	s_add_i32 s44, s19, 48
	s_and_b32 s44, s44, 0xfff
	v_or_b32_e32 v0, s44, v141
	v_lshlrev_b32_e32 v0, 6, v0
	global_load_dwordx4 v[218:221], v0, s[62:63]
	global_load_dwordx4 v[222:225], v0, s[62:63] offset:16
	global_load_dwordx4 v[226:229], v0, s[62:63] offset:32
	global_load_dwordx4 v[230:233], v0, s[62:63] offset:48
	v_pk_mul_f32 v[86:87], v[86:87], v[150:151] op_sel_hi:[1,0]
	v_pk_mul_f32 v[88:89], v[88:89], v[150:151] op_sel_hi:[1,0]
	v_pk_mul_f32 v[82:83], v[82:83], v[150:151] op_sel_hi:[1,0]
	v_pk_mul_f32 v[84:85], v[84:85], v[150:151] op_sel_hi:[1,0]
	v_pk_mul_f32 v[86:87], v[86:87], s[30:31] op_sel_hi:[1,0]
	v_pk_mul_f32 v[88:89], v[88:89], s[30:31] op_sel_hi:[1,0]
	v_pk_mul_f32 v[82:83], v[82:83], s[30:31] op_sel_hi:[1,0]
	v_pk_mul_f32 v[84:85], v[84:85], s[30:31] op_sel_hi:[1,0]
	v_cvt_pk_bf16_f32 v86, v86, v87
	v_cvt_pk_bf16_f32 v87, v88, v89
	v_cvt_pk_bf16_f32 v88, v82, v83
	v_cvt_pk_bf16_f32 v89, v84, v85
	v_pk_mul_f32 v[94:95], v[94:95], v[150:151] op_sel_hi:[1,0]
	v_pk_mul_f32 v[96:97], v[96:97], v[150:151] op_sel_hi:[1,0]
	v_pk_mul_f32 v[90:91], v[90:91], v[150:151] op_sel_hi:[1,0]
	v_pk_mul_f32 v[92:93], v[92:93], v[150:151] op_sel_hi:[1,0]
	ds_swizzle_b32 v82, v94 offset:0x401f
	ds_swizzle_b32 v83, v95 offset:0x401f
	ds_swizzle_b32 v84, v96 offset:0x401f
	ds_swizzle_b32 v85, v97 offset:0x401f
	s_waitcnt vmcnt(6)
	v_xor_b32_e32 v162, v201, v162
	v_xor_b32_e32 v163, v201, v163
	v_xor_b32_e32 v164, v201, v164
	v_xor_b32_e32 v165, v201, v165
	v_xor_b32_e32 v166, v201, v166
	v_xor_b32_e32 v167, v201, v167
	v_xor_b32_e32 v168, v201, v168
	v_xor_b32_e32 v169, v201, v169
	s_waitcnt lgkmcnt(0)
	v_mul_f32_e32 v82, v162, v82
	v_fmac_f32_e32 v82, v94, v154
	v_cndmask_b32_e64 v94, v94, v82, s[38:39]
	v_mul_f32_e32 v83, v163, v83
	v_fmac_f32_e32 v83, v95, v155
	v_cndmask_b32_e64 v95, v95, v83, s[38:39]
	v_mul_f32_e32 v84, v164, v84
	v_fmac_f32_e32 v84, v96, v156
	v_cndmask_b32_e64 v96, v96, v84, s[38:39]
	v_mul_f32_e32 v85, v165, v85
	v_fmac_f32_e32 v85, v97, v157
	v_cndmask_b32_e64 v97, v97, v85, s[38:39]
	ds_swizzle_b32 v82, v90 offset:0x401f
	ds_swizzle_b32 v83, v91 offset:0x401f
	ds_swizzle_b32 v84, v92 offset:0x401f
	ds_swizzle_b32 v85, v93 offset:0x401f
	s_waitcnt lgkmcnt(0)
	v_mul_f32_e32 v82, v166, v82
	v_fmac_f32_e32 v82, v90, v158
	v_cndmask_b32_e64 v90, v90, v82, s[38:39]
	v_mul_f32_e32 v83, v167, v83
	v_fmac_f32_e32 v83, v91, v159
	v_cndmask_b32_e64 v91, v91, v83, s[38:39]
	v_mul_f32_e32 v84, v168, v84
	v_fmac_f32_e32 v84, v92, v160
	v_cndmask_b32_e64 v92, v92, v84, s[38:39]
	v_mul_f32_e32 v85, v169, v85
	v_fmac_f32_e32 v85, v93, v161
	v_cndmask_b32_e64 v93, v93, v85, s[38:39]
	v_pk_mul_f32 v[94:95], v[94:95], s[30:31] op_sel_hi:[1,0]
	v_pk_mul_f32 v[96:97], v[96:97], s[30:31] op_sel_hi:[1,0]
	v_pk_mul_f32 v[90:91], v[90:91], s[30:31] op_sel_hi:[1,0]
	v_pk_mul_f32 v[92:93], v[92:93], s[30:31] op_sel_hi:[1,0]
	v_cvt_pk_bf16_f32 v94, v94, v95
	v_cvt_pk_bf16_f32 v95, v96, v97
	v_cvt_pk_bf16_f32 v96, v90, v91
	v_cvt_pk_bf16_f32 v97, v92, v93
	s_mul_i32 s44, s66, 16
	s_add_u32 s100, s98, s44
	s_addc_u32 s101, s99, 0
	global_store_dwordx4 v200, v[106:109], s[100:101] nt
	s_add_u32 s100, s100, s67
	s_addc_u32 s101, s101, 0
	global_store_dwordx4 v200, v[98:101], s[100:101] nt
	ds_write_b128 v178, v[94:97]
	ds_write_b128 v178, v[86:89] offset:64
	ds_read_b128 v[90:93], v180
	ds_read_b128 v[82:85], v180 offset:1152
	s_add_i32 s44, s19, 128
	s_and_b32 s44, s44, 0xfff
	v_or_b32_e32 v0, s44, v141
	v_lshlrev_b32_e32 v0, 6, v0
	global_load_dwordx4 v[154:157], v0, s[62:63]
	global_load_dwordx4 v[158:161], v0, s[62:63] offset:16
	global_load_dwordx4 v[162:165], v0, s[62:63] offset:32
	global_load_dwordx4 v[166:169], v0, s[62:63] offset:48
	v_pk_mul_f32 v[70:71], v[70:71], v[150:151] op_sel:[0,1]
	v_pk_mul_f32 v[72:73], v[72:73], v[150:151] op_sel:[0,1]
	v_pk_mul_f32 v[66:67], v[66:67], v[150:151] op_sel:[0,1]
	v_pk_mul_f32 v[68:69], v[68:69], v[150:151] op_sel:[0,1]
	v_pk_mul_f32 v[70:71], v[70:71], s[30:31] op_sel_hi:[1,0]
	v_pk_mul_f32 v[72:73], v[72:73], s[30:31] op_sel_hi:[1,0]
	v_pk_mul_f32 v[66:67], v[66:67], s[30:31] op_sel_hi:[1,0]
	v_pk_mul_f32 v[68:69], v[68:69], s[30:31] op_sel_hi:[1,0]
	v_cvt_pk_bf16_f32 v70, v70, v71
	v_cvt_pk_bf16_f32 v71, v72, v73
	v_cvt_pk_bf16_f32 v72, v66, v67
	v_cvt_pk_bf16_f32 v73, v68, v69
	v_pk_mul_f32 v[78:79], v[78:79], v[150:151] op_sel:[0,1]
	v_pk_mul_f32 v[80:81], v[80:81], v[150:151] op_sel:[0,1]
	v_pk_mul_f32 v[74:75], v[74:75], v[150:151] op_sel:[0,1]
	v_pk_mul_f32 v[76:77], v[76:77], v[150:151] op_sel:[0,1]
	ds_swizzle_b32 v66, v78 offset:0x401f
	ds_swizzle_b32 v67, v79 offset:0x401f
	ds_swizzle_b32 v68, v80 offset:0x401f
	ds_swizzle_b32 v69, v81 offset:0x401f
	s_waitcnt vmcnt(6)
;     __device__ __forceinline__ void operator()(const f32x4 (&acc)[2][2][4][2], const Unit& u, int wr, int wc, int fr, int fq, PG8_LAS float* stash, int par, PG8_LAS unsigned char* stg, const Unit& un) const {
;     ...
;                     for (int i = 0; i < 4; ++i) { v[i] = acc[ai][bj][m][0][i] * rs; v[4 + i] = acc[ai][bj][m][1][i] * rs; }
;                     if (kind <= 1 && bj == 0) {
;                         const f32x4 c0 = *(const f32x4*)(cs + pos * 16), c1 = *(const f32x4*)(cs + pos * 16 + 4), s0 = *(const f32x4*)(cs + pos * 16 + 8), s1 = *(const f32x4*)(cs + pos * 16 + 12);
; #pragma unroll
;                         for (int i = 0; i < 8; ++i) {
;                             const float c = i < 4 ? c0[i & 3] : c1[i & 3], s = i < 4 ? s0[i & 3] : s1[i & 3];
;                             const float pr = peer_x16(v[i], fq);
;                             const float r = (fq == 0) ? (v[i] * c - pr * s) : (v[i] * c + pr * s);
;                             v[i] = (fq < 2) ? r : v[i];
;                         }
;                     }
;                     if (kind == 0) {
; #pragma unroll
;                         for (int i = 0; i < 8; ++i) v[i] *= C2Q;
;                     }
;                     { u32x4 w; w.x = cvt_pk_bf16(v[0], v[1]); w.y = cvt_pk_bf16(v[2], v[3]); w.z = cvt_pk_bf16(v[4], v[5]); w.w = cvt_pk_bf16(v[6], v[7]);
;                       *(PG8_LAS u32x4*)(stg + fr * 144 + fq * 16 + bj * 64) = w; }
;                 }
;                 {
;                     int kind;
;                     if (odd) kind = (u.pn < 6) ? 0 : (u.pn == 6 ? 1 : 2);
;                     else     kind = (u.pn < 2) ? 0 : (u.pn == 2 ? (wc < 2 ? 1 : 2) : 3);
; #pragma unroll
;                     for (int i = 0; i < 2; ++i) { const int c = fq * 16 + fr + 64 * i, rr = c >> 3, pc = c & 7;
;                         const u32x4 w = *(const PG8_LAS u32x4*)(stg + rr * 144 + pc * 16);
;                         const int rowc = row - fr + rr, posc = rowc & 4095;
;                         if (kind == 1 || kind == 2) {
;                             bf16_t* dst = (kind == 1) ? kd : vt;
;                             if (odd) *(u32x4*)(dst + (size_t)(b * 4 + wc) * (4096 * 64) + (size_t)((posc & 15) * 256 + (posc >> 4)) * 64 + pc * 8) = w;
;                             else     *(u32x4*)(dst + (size_t)(b * 2 + (wc & 1)) * (4096 * 64) + (size_t)posc * 64 + pc * 8) = w;
	v_xor_b32_e32 v226, v201, v226
	v_xor_b32_e32 v227, v201, v227
	v_xor_b32_e32 v228, v201, v228
	v_xor_b32_e32 v229, v201, v229
	v_xor_b32_e32 v230, v201, v230
	v_xor_b32_e32 v231, v201, v231
	v_xor_b32_e32 v232, v201, v232
	v_xor_b32_e32 v233, v201, v233
	s_waitcnt lgkmcnt(0)
	v_mul_f32_e32 v66, v226, v66
	v_fmac_f32_e32 v66, v78, v218
	v_cndmask_b32_e64 v78, v78, v66, s[38:39]
	v_mul_f32_e32 v67, v227, v67
	v_fmac_f32_e32 v67, v79, v219
	v_cndmask_b32_e64 v79, v79, v67, s[38:39]
	v_mul_f32_e32 v68, v228, v68
	v_fmac_f32_e32 v68, v80, v220
	v_cndmask_b32_e64 v80, v80, v68, s[38:39]
	v_mul_f32_e32 v69, v229, v69
	v_fmac_f32_e32 v69, v81, v221
	v_cndmask_b32_e64 v81, v81, v69, s[38:39]
	ds_swizzle_b32 v66, v74 offset:0x401f
	ds_swizzle_b32 v67, v75 offset:0x401f
	ds_swizzle_b32 v68, v76 offset:0x401f
	ds_swizzle_b32 v69, v77 offset:0x401f
	s_waitcnt lgkmcnt(0)
	v_mul_f32_e32 v66, v230, v66
	v_fmac_f32_e32 v66, v74, v222
	v_cndmask_b32_e64 v74, v74, v66, s[38:39]
	v_mul_f32_e32 v67, v231, v67
	v_fmac_f32_e32 v67, v75, v223
	v_cndmask_b32_e64 v75, v75, v67, s[38:39]
	v_mul_f32_e32 v68, v232, v68
	v_fmac_f32_e32 v68, v76, v224
	v_cndmask_b32_e64 v76, v76, v68, s[38:39]
	v_mul_f32_e32 v69, v233, v69
	v_fmac_f32_e32 v69, v77, v225
	v_cndmask_b32_e64 v77, v77, v69, s[38:39]
	v_pk_mul_f32 v[78:79], v[78:79], s[30:31] op_sel_hi:[1,0]
	v_pk_mul_f32 v[80:81], v[80:81], s[30:31] op_sel_hi:[1,0]
	v_pk_mul_f32 v[74:75], v[74:75], s[30:31] op_sel_hi:[1,0]
	v_pk_mul_f32 v[76:77], v[76:77], s[30:31] op_sel_hi:[1,0]
	v_cvt_pk_bf16_f32 v78, v78, v79
	v_cvt_pk_bf16_f32 v79, v80, v81
	v_cvt_pk_bf16_f32 v80, v74, v75
	v_cvt_pk_bf16_f32 v81, v76, v77
	s_mul_i32 s44, s66, 32
	s_add_u32 s100, s98, s44
	s_addc_u32 s101, s99, 0
	global_store_dwordx4 v200, v[90:93], s[100:101] nt
	s_add_u32 s100, s100, s67
	s_addc_u32 s101, s101, 0
	global_store_dwordx4 v200, v[82:85], s[100:101] nt
	ds_write_b128 v178, v[78:81]
	ds_write_b128 v178, v[70:73] offset:64
	ds_read_b128 v[74:77], v180
	ds_read_b128 v[66:69], v180 offset:1152
	s_add_i32 s44, s19, 144
	s_and_b32 s44, s44, 0xfff
	v_or_b32_e32 v0, s44, v141
	v_lshlrev_b32_e32 v0, 6, v0
	global_load_dwordx4 v[218:221], v0, s[62:63]
	global_load_dwordx4 v[222:225], v0, s[62:63] offset:16
	global_load_dwordx4 v[226:229], v0, s[62:63] offset:32
	global_load_dwordx4 v[230:233], v0, s[62:63] offset:48
	v_pk_mul_f32 v[54:55], v[54:55], v[148:149] op_sel_hi:[1,0]
	v_pk_mul_f32 v[56:57], v[56:57], v[148:149] op_sel_hi:[1,0]
	v_pk_mul_f32 v[50:51], v[50:51], v[148:149] op_sel_hi:[1,0]
	v_pk_mul_f32 v[52:53], v[52:53], v[148:149] op_sel_hi:[1,0]
	v_pk_mul_f32 v[54:55], v[54:55], s[30:31] op_sel_hi:[1,0]
	v_pk_mul_f32 v[56:57], v[56:57], s[30:31] op_sel_hi:[1,0]
	v_pk_mul_f32 v[50:51], v[50:51], s[30:31] op_sel_hi:[1,0]
	v_pk_mul_f32 v[52:53], v[52:53], s[30:31] op_sel_hi:[1,0]
	v_cvt_pk_bf16_f32 v54, v54, v55
	v_cvt_pk_bf16_f32 v55, v56, v57
	v_cvt_pk_bf16_f32 v56, v50, v51
	v_cvt_pk_bf16_f32 v57, v52, v53
	v_pk_mul_f32 v[62:63], v[62:63], v[148:149] op_sel_hi:[1,0]
	v_pk_mul_f32 v[64:65], v[64:65], v[148:149] op_sel_hi:[1,0]
	v_pk_mul_f32 v[58:59], v[58:59], v[148:149] op_sel_hi:[1,0]
	v_pk_mul_f32 v[60:61], v[60:61], v[148:149] op_sel_hi:[1,0]
	ds_swizzle_b32 v50, v62 offset:0x401f
	ds_swizzle_b32 v51, v63 offset:0x401f
	ds_swizzle_b32 v52, v64 offset:0x401f
	ds_swizzle_b32 v53, v65 offset:0x401f
	s_waitcnt vmcnt(6)
	v_xor_b32_e32 v162, v201, v162
	v_xor_b32_e32 v163, v201, v163
	v_xor_b32_e32 v164, v201, v164
	v_xor_b32_e32 v165, v201, v165
	v_xor_b32_e32 v166, v201, v166
	v_xor_b32_e32 v167, v201, v167
	v_xor_b32_e32 v168, v201, v168
	v_xor_b32_e32 v169, v201, v169
	s_waitcnt lgkmcnt(0)
	v_mul_f32_e32 v50, v162, v50
	v_fmac_f32_e32 v50, v62, v154
	v_cndmask_b32_e64 v62, v62, v50, s[38:39]
	v_mul_f32_e32 v51, v163, v51
	v_fmac_f32_e32 v51, v63, v155
	v_cndmask_b32_e64 v63, v63, v51, s[38:39]
	v_mul_f32_e32 v52, v164, v52
	v_fmac_f32_e32 v52, v64, v156
	v_cndmask_b32_e64 v64, v64, v52, s[38:39]
	v_mul_f32_e32 v53, v165, v53
	v_fmac_f32_e32 v53, v65, v157
	v_cndmask_b32_e64 v65, v65, v53, s[38:39]
	ds_swizzle_b32 v50, v58 offset:0x401f
	ds_swizzle_b32 v51, v59 offset:0x401f
	ds_swizzle_b32 v52, v60 offset:0x401f
	ds_swizzle_b32 v53, v61 offset:0x401f
	s_waitcnt lgkmcnt(0)
	v_mul_f32_e32 v50, v166, v50
	v_fmac_f32_e32 v50, v58, v158
	v_cndmask_b32_e64 v58, v58, v50, s[38:39]
	v_mul_f32_e32 v51, v167, v51
	v_fmac_f32_e32 v51, v59, v159
	v_cndmask_b32_e64 v59, v59, v51, s[38:39]
	v_mul_f32_e32 v52, v168, v52
	v_fmac_f32_e32 v52, v60, v160
	v_cndmask_b32_e64 v60, v60, v52, s[38:39]
	v_mul_f32_e32 v53, v169, v53
	v_fmac_f32_e32 v53, v61, v161
	v_cndmask_b32_e64 v61, v61, v53, s[38:39]
	v_pk_mul_f32 v[62:63], v[62:63], s[30:31] op_sel_hi:[1,0]
	v_pk_mul_f32 v[64:65], v[64:65], s[30:31] op_sel_hi:[1,0]
	v_pk_mul_f32 v[58:59], v[58:59], s[30:31] op_sel_hi:[1,0]
	v_pk_mul_f32 v[60:61], v[60:61], s[30:31] op_sel_hi:[1,0]
	v_cvt_pk_bf16_f32 v62, v62, v63
	v_cvt_pk_bf16_f32 v63, v64, v65
	v_cvt_pk_bf16_f32 v64, v58, v59
	v_cvt_pk_bf16_f32 v65, v60, v61
	s_mul_i32 s44, s66, 48
	s_add_u32 s100, s98, s44
	s_addc_u32 s101, s99, 0
	global_store_dwordx4 v200, v[74:77], s[100:101] nt
	s_add_u32 s100, s100, s67
	s_addc_u32 s101, s101, 0
	global_store_dwordx4 v200, v[66:69], s[100:101] nt
	ds_write_b128 v178, v[62:65]
	ds_write_b128 v178, v[54:57] offset:64
	ds_read_b128 v[58:61], v180
	ds_read_b128 v[50:53], v180 offset:1152
	s_add_i32 s44, s19, 160
	s_and_b32 s44, s44, 0xfff
	v_or_b32_e32 v0, s44, v141
	v_lshlrev_b32_e32 v0, 6, v0
	global_load_dwordx4 v[154:157], v0, s[62:63]
	global_load_dwordx4 v[158:161], v0, s[62:63] offset:16
	global_load_dwordx4 v[162:165], v0, s[62:63] offset:32
	global_load_dwordx4 v[166:169], v0, s[62:63] offset:48
	v_pk_mul_f32 v[38:39], v[38:39], v[148:149] op_sel:[0,1]
	v_pk_mul_f32 v[40:41], v[40:41], v[148:149] op_sel:[0,1]
	v_pk_mul_f32 v[34:35], v[34:35], v[148:149] op_sel:[0,1]
	v_pk_mul_f32 v[36:37], v[36:37], v[148:149] op_sel:[0,1]
	v_pk_mul_f32 v[38:39], v[38:39], s[30:31] op_sel_hi:[1,0]
	v_pk_mul_f32 v[40:41], v[40:41], s[30:31] op_sel_hi:[1,0]
	v_pk_mul_f32 v[34:35], v[34:35], s[30:31] op_sel_hi:[1,0]
	v_pk_mul_f32 v[36:37], v[36:37], s[30:31] op_sel_hi:[1,0]
	v_cvt_pk_bf16_f32 v38, v38, v39
	v_cvt_pk_bf16_f32 v39, v40, v41
	v_cvt_pk_bf16_f32 v40, v34, v35
	v_cvt_pk_bf16_f32 v41, v36, v37
	v_pk_mul_f32 v[46:47], v[46:47], v[148:149] op_sel:[0,1]
	v_pk_mul_f32 v[48:49], v[48:49], v[148:149] op_sel:[0,1]
	v_pk_mul_f32 v[42:43], v[42:43], v[148:149] op_sel:[0,1]
	v_pk_mul_f32 v[44:45], v[44:45], v[148:149] op_sel:[0,1]
	ds_swizzle_b32 v34, v46 offset:0x401f
	ds_swizzle_b32 v35, v47 offset:0x401f
	ds_swizzle_b32 v36, v48 offset:0x401f
	ds_swizzle_b32 v37, v49 offset:0x401f
	s_waitcnt vmcnt(6)
;     __device__ __forceinline__ void operator()(const f32x4 (&acc)[2][2][4][2], const Unit& u, int wr, int wc, int fr, int fq, PG8_LAS float* stash, int par, PG8_LAS unsigned char* stg, const Unit& un) const {
;     ...
;                     for (int i = 0; i < 4; ++i) { v[i] = acc[ai][bj][m][0][i] * rs; v[4 + i] = acc[ai][bj][m][1][i] * rs; }
;                     if (kind <= 1 && bj == 0) {
;                         const f32x4 c0 = *(const f32x4*)(cs + pos * 16), c1 = *(const f32x4*)(cs + pos * 16 + 4), s0 = *(const f32x4*)(cs + pos * 16 + 8), s1 = *(const f32x4*)(cs + pos * 16 + 12);
; #pragma unroll
;                         for (int i = 0; i < 8; ++i) {
;                             const float c = i < 4 ? c0[i & 3] : c1[i & 3], s = i < 4 ? s0[i & 3] : s1[i & 3];
;                             const float pr = peer_x16(v[i], fq);
;                             const float r = (fq == 0) ? (v[i] * c - pr * s) : (v[i] * c + pr * s);
;                             v[i] = (fq < 2) ? r : v[i];
;                         }
;                     }
;                     if (kind == 0) {
; #pragma unroll
;                         for (int i = 0; i < 8; ++i) v[i] *= C2Q;
;                     }
;                     { u32x4 w; w.x = cvt_pk_bf16(v[0], v[1]); w.y = cvt_pk_bf16(v[2], v[3]); w.z = cvt_pk_bf16(v[4], v[5]); w.w = cvt_pk_bf16(v[6], v[7]);
;                       *(PG8_LAS u32x4*)(stg + fr * 144 + fq * 16 + bj * 64) = w; }
;                 }
;                 {
;                     int kind;
;                     if (odd) kind = (u.pn < 6) ? 0 : (u.pn == 6 ? 1 : 2);
;                     else     kind = (u.pn < 2) ? 0 : (u.pn == 2 ? (wc < 2 ? 1 : 2) : 3);
; #pragma unroll
;                     for (int i = 0; i < 2; ++i) { const int c = fq * 16 + fr + 64 * i, rr = c >> 3, pc = c & 7;
;                         const u32x4 w = *(const PG8_LAS u32x4*)(stg + rr * 144 + pc * 16);
;                         const int rowc = row - fr + rr, posc = rowc & 4095;
;                         if (kind == 1 || kind == 2) {
;                             bf16_t* dst = (kind == 1) ? kd : vt;
;                             if (odd) *(u32x4*)(dst + (size_t)(b * 4 + wc) * (4096 * 64) + (size_t)((posc & 15) * 256 + (posc >> 4)) * 64 + pc * 8) = w;
;                             else     *(u32x4*)(dst + (size_t)(b * 2 + (wc & 1)) * (4096 * 64) + (size_t)posc * 64 + pc * 8) = w;
	v_xor_b32_e32 v226, v201, v226
	v_xor_b32_e32 v227, v201, v227
	v_xor_b32_e32 v228, v201, v228
	v_xor_b32_e32 v229, v201, v229
	v_xor_b32_e32 v230, v201, v230
	v_xor_b32_e32 v231, v201, v231
	v_xor_b32_e32 v232, v201, v232
	v_xor_b32_e32 v233, v201, v233
	s_waitcnt lgkmcnt(0)
	v_mul_f32_e32 v34, v226, v34
	v_fmac_f32_e32 v34, v46, v218
	v_cndmask_b32_e64 v46, v46, v34, s[38:39]
	v_mul_f32_e32 v35, v227, v35
	v_fmac_f32_e32 v35, v47, v219
	v_cndmask_b32_e64 v47, v47, v35, s[38:39]
	v_mul_f32_e32 v36, v228, v36
	v_fmac_f32_e32 v36, v48, v220
	v_cndmask_b32_e64 v48, v48, v36, s[38:39]
	v_mul_f32_e32 v37, v229, v37
	v_fmac_f32_e32 v37, v49, v221
	v_cndmask_b32_e64 v49, v49, v37, s[38:39]
	ds_swizzle_b32 v34, v42 offset:0x401f
	ds_swizzle_b32 v35, v43 offset:0x401f
	ds_swizzle_b32 v36, v44 offset:0x401f
	ds_swizzle_b32 v37, v45 offset:0x401f
	s_waitcnt lgkmcnt(0)
	v_mul_f32_e32 v34, v230, v34
	v_fmac_f32_e32 v34, v42, v222
	v_cndmask_b32_e64 v42, v42, v34, s[38:39]
	v_mul_f32_e32 v35, v231, v35
	v_fmac_f32_e32 v35, v43, v223
	v_cndmask_b32_e64 v43, v43, v35, s[38:39]
	v_mul_f32_e32 v36, v232, v36
	v_fmac_f32_e32 v36, v44, v224
	v_cndmask_b32_e64 v44, v44, v36, s[38:39]
	v_mul_f32_e32 v37, v233, v37
	v_fmac_f32_e32 v37, v45, v225
	v_cndmask_b32_e64 v45, v45, v37, s[38:39]
	v_pk_mul_f32 v[46:47], v[46:47], s[30:31] op_sel_hi:[1,0]
	v_pk_mul_f32 v[48:49], v[48:49], s[30:31] op_sel_hi:[1,0]
	v_pk_mul_f32 v[42:43], v[42:43], s[30:31] op_sel_hi:[1,0]
	v_pk_mul_f32 v[44:45], v[44:45], s[30:31] op_sel_hi:[1,0]
	v_cvt_pk_bf16_f32 v46, v46, v47
	v_cvt_pk_bf16_f32 v47, v48, v49
	v_cvt_pk_bf16_f32 v48, v42, v43
	v_cvt_pk_bf16_f32 v49, v44, v45
	s_mul_i32 s44, s66, 128
	s_add_u32 s100, s98, s44
	s_addc_u32 s101, s99, 0
	global_store_dwordx4 v200, v[58:61], s[100:101] nt
	s_add_u32 s100, s100, s67
	s_addc_u32 s101, s101, 0
	global_store_dwordx4 v200, v[50:53], s[100:101] nt
	ds_write_b128 v178, v[46:49]
	ds_write_b128 v178, v[38:41] offset:64
	ds_read_b128 v[42:45], v180
	ds_read_b128 v[34:37], v180 offset:1152
	s_add_i32 s44, s19, 176
	s_and_b32 s44, s44, 0xfff
	v_or_b32_e32 v0, s44, v141
	v_lshlrev_b32_e32 v0, 6, v0
	global_load_dwordx4 v[218:221], v0, s[62:63]
	global_load_dwordx4 v[222:225], v0, s[62:63] offset:16
	global_load_dwordx4 v[226:229], v0, s[62:63] offset:32
	global_load_dwordx4 v[230:233], v0, s[62:63] offset:48
	v_pk_mul_f32 v[22:23], v[22:23], v[146:147] op_sel_hi:[1,0]
	v_pk_mul_f32 v[24:25], v[24:25], v[146:147] op_sel_hi:[1,0]
	v_pk_mul_f32 v[18:19], v[18:19], v[146:147] op_sel_hi:[1,0]
	v_pk_mul_f32 v[20:21], v[20:21], v[146:147] op_sel_hi:[1,0]
	v_pk_mul_f32 v[22:23], v[22:23], s[30:31] op_sel_hi:[1,0]
	v_pk_mul_f32 v[24:25], v[24:25], s[30:31] op_sel_hi:[1,0]
	v_pk_mul_f32 v[18:19], v[18:19], s[30:31] op_sel_hi:[1,0]
	v_pk_mul_f32 v[20:21], v[20:21], s[30:31] op_sel_hi:[1,0]
	v_cvt_pk_bf16_f32 v22, v22, v23
	v_cvt_pk_bf16_f32 v23, v24, v25
	v_cvt_pk_bf16_f32 v24, v18, v19
	v_cvt_pk_bf16_f32 v25, v20, v21
	v_pk_mul_f32 v[30:31], v[30:31], v[146:147] op_sel_hi:[1,0]
	v_pk_mul_f32 v[32:33], v[32:33], v[146:147] op_sel_hi:[1,0]
	v_pk_mul_f32 v[26:27], v[26:27], v[146:147] op_sel_hi:[1,0]
	v_pk_mul_f32 v[28:29], v[28:29], v[146:147] op_sel_hi:[1,0]
	ds_swizzle_b32 v18, v30 offset:0x401f
	ds_swizzle_b32 v19, v31 offset:0x401f
	ds_swizzle_b32 v20, v32 offset:0x401f
	ds_swizzle_b32 v21, v33 offset:0x401f
	s_waitcnt vmcnt(6)
	v_xor_b32_e32 v162, v201, v162
	v_xor_b32_e32 v163, v201, v163
	v_xor_b32_e32 v164, v201, v164
	v_xor_b32_e32 v165, v201, v165
	v_xor_b32_e32 v166, v201, v166
	v_xor_b32_e32 v167, v201, v167
	v_xor_b32_e32 v168, v201, v168
	v_xor_b32_e32 v169, v201, v169
	s_waitcnt lgkmcnt(0)
	v_mul_f32_e32 v18, v162, v18
	v_fmac_f32_e32 v18, v30, v154
	v_cndmask_b32_e64 v30, v30, v18, s[38:39]
	v_mul_f32_e32 v19, v163, v19
	v_fmac_f32_e32 v19, v31, v155
	v_cndmask_b32_e64 v31, v31, v19, s[38:39]
	v_mul_f32_e32 v20, v164, v20
	v_fmac_f32_e32 v20, v32, v156
	v_cndmask_b32_e64 v32, v32, v20, s[38:39]
	v_mul_f32_e32 v21, v165, v21
	v_fmac_f32_e32 v21, v33, v157
	v_cndmask_b32_e64 v33, v33, v21, s[38:39]
	ds_swizzle_b32 v18, v26 offset:0x401f
	ds_swizzle_b32 v19, v27 offset:0x401f
	ds_swizzle_b32 v20, v28 offset:0x401f
	ds_swizzle_b32 v21, v29 offset:0x401f
	s_waitcnt lgkmcnt(0)
	v_mul_f32_e32 v18, v166, v18
	v_fmac_f32_e32 v18, v26, v158
	v_cndmask_b32_e64 v26, v26, v18, s[38:39]
	v_mul_f32_e32 v19, v167, v19
	v_fmac_f32_e32 v19, v27, v159
	v_cndmask_b32_e64 v27, v27, v19, s[38:39]
	v_mul_f32_e32 v20, v168, v20
	v_fmac_f32_e32 v20, v28, v160
	v_cndmask_b32_e64 v28, v28, v20, s[38:39]
	v_mul_f32_e32 v21, v169, v21
	v_fmac_f32_e32 v21, v29, v161
	v_cndmask_b32_e64 v29, v29, v21, s[38:39]
	v_pk_mul_f32 v[30:31], v[30:31], s[30:31] op_sel_hi:[1,0]
	v_pk_mul_f32 v[32:33], v[32:33], s[30:31] op_sel_hi:[1,0]
	v_pk_mul_f32 v[26:27], v[26:27], s[30:31] op_sel_hi:[1,0]
	v_pk_mul_f32 v[28:29], v[28:29], s[30:31] op_sel_hi:[1,0]
	v_cvt_pk_bf16_f32 v30, v30, v31
	v_cvt_pk_bf16_f32 v31, v32, v33
	v_cvt_pk_bf16_f32 v32, v26, v27
	v_cvt_pk_bf16_f32 v33, v28, v29
	s_mul_i32 s44, s66, 144
	s_add_u32 s100, s98, s44
	s_addc_u32 s101, s99, 0
	global_store_dwordx4 v200, v[42:45], s[100:101] nt
	s_add_u32 s100, s100, s67
	s_addc_u32 s101, s101, 0
	global_store_dwordx4 v200, v[34:37], s[100:101] nt
	ds_write_b128 v178, v[30:33]
	ds_write_b128 v178, v[22:25] offset:64
	ds_read_b128 v[26:29], v180
	ds_read_b128 v[18:21], v180 offset:1152
	v_pk_mul_f32 v[6:7], v[6:7], v[146:147] op_sel:[0,1]
	v_pk_mul_f32 v[8:9], v[8:9], v[146:147] op_sel:[0,1]
	v_pk_mul_f32 v[2:3], v[2:3], v[146:147] op_sel:[0,1]
	v_pk_mul_f32 v[4:5], v[4:5], v[146:147] op_sel:[0,1]
	v_pk_mul_f32 v[6:7], v[6:7], s[30:31] op_sel_hi:[1,0]
	v_pk_mul_f32 v[8:9], v[8:9], s[30:31] op_sel_hi:[1,0]
	v_pk_mul_f32 v[2:3], v[2:3], s[30:31] op_sel_hi:[1,0]
	v_pk_mul_f32 v[4:5], v[4:5], s[30:31] op_sel_hi:[1,0]
	v_cvt_pk_bf16_f32 v6, v6, v7
	v_cvt_pk_bf16_f32 v7, v8, v9
	v_cvt_pk_bf16_f32 v8, v2, v3
	v_cvt_pk_bf16_f32 v9, v4, v5
	v_pk_mul_f32 v[14:15], v[14:15], v[146:147] op_sel:[0,1]
	v_pk_mul_f32 v[16:17], v[16:17], v[146:147] op_sel:[0,1]
	v_pk_mul_f32 v[10:11], v[10:11], v[146:147] op_sel:[0,1]
	v_pk_mul_f32 v[12:13], v[12:13], v[146:147] op_sel:[0,1]
	ds_swizzle_b32 v2, v14 offset:0x401f
	ds_swizzle_b32 v3, v15 offset:0x401f
	ds_swizzle_b32 v4, v16 offset:0x401f
	ds_swizzle_b32 v5, v17 offset:0x401f
	s_waitcnt vmcnt(2)
;     __device__ __forceinline__ void operator()(const f32x4 (&acc)[2][2][4][2], const Unit& u, int wr, int wc, int fr, int fq, PG8_LAS float* stash, int par, PG8_LAS unsigned char* stg, const Unit& un) const {
;     ...
;                     for (int i = 0; i < 4; ++i) { v[i] = acc[ai][bj][m][0][i] * rs; v[4 + i] = acc[ai][bj][m][1][i] * rs; }
;                     if (kind <= 1 && bj == 0) {
;                         const f32x4 c0 = *(const f32x4*)(cs + pos * 16), c1 = *(const f32x4*)(cs + pos * 16 + 4), s0 = *(const f32x4*)(cs + pos * 16 + 8), s1 = *(const f32x4*)(cs + pos * 16 + 12);
; #pragma unroll
;                         for (int i = 0; i < 8; ++i) {
;                             const float c = i < 4 ? c0[i & 3] : c1[i & 3], s = i < 4 ? s0[i & 3] : s1[i & 3];
;                             const float pr = peer_x16(v[i], fq);
;                             const float r = (fq == 0) ? (v[i] * c - pr * s) : (v[i] * c + pr * s);
;                             v[i] = (fq < 2) ? r : v[i];
;                         }
;                     }
;                     if (kind == 0) {
; #pragma unroll
;                         for (int i = 0; i < 8; ++i) v[i] *= C2Q;
;                     }
;                     { u32x4 w; w.x = cvt_pk_bf16(v[0], v[1]); w.y = cvt_pk_bf16(v[2], v[3]); w.z = cvt_pk_bf16(v[4], v[5]); w.w = cvt_pk_bf16(v[6], v[7]);
;                       *(PG8_LAS u32x4*)(stg + fr * 144 + fq * 16 + bj * 64) = w; }
;                 }
;                 {
;                     int kind;
;                     if (odd) kind = (u.pn < 6) ? 0 : (u.pn == 6 ? 1 : 2);
;                     else     kind = (u.pn < 2) ? 0 : (u.pn == 2 ? (wc < 2 ? 1 : 2) : 3);
; #pragma unroll
;                     for (int i = 0; i < 2; ++i) { const int c = fq * 16 + fr + 64 * i, rr = c >> 3, pc = c & 7;
;                         const u32x4 w = *(const PG8_LAS u32x4*)(stg + rr * 144 + pc * 16);
;                         const int rowc = row - fr + rr, posc = rowc & 4095;
;                         if (kind == 1 || kind == 2) {
;                             bf16_t* dst = (kind == 1) ? kd : vt;
;                             if (odd) *(u32x4*)(dst + (size_t)(b * 4 + wc) * (4096 * 64) + (size_t)((posc & 15) * 256 + (posc >> 4)) * 64 + pc * 8) = w;
;                             else     *(u32x4*)(dst + (size_t)(b * 2 + (wc & 1)) * (4096 * 64) + (size_t)posc * 64 + pc * 8) = w;
	v_xor_b32_e32 v226, v201, v226
	v_xor_b32_e32 v227, v201, v227
	v_xor_b32_e32 v228, v201, v228
	v_xor_b32_e32 v229, v201, v229
	v_xor_b32_e32 v230, v201, v230
	v_xor_b32_e32 v231, v201, v231
	v_xor_b32_e32 v232, v201, v232
	v_xor_b32_e32 v233, v201, v233
	s_waitcnt lgkmcnt(0)
	v_mul_f32_e32 v2, v226, v2
	v_fmac_f32_e32 v2, v14, v218
	v_cndmask_b32_e64 v14, v14, v2, s[38:39]
	v_mul_f32_e32 v3, v227, v3
	v_fmac_f32_e32 v3, v15, v219
	v_cndmask_b32_e64 v15, v15, v3, s[38:39]
	v_mul_f32_e32 v4, v228, v4
	v_fmac_f32_e32 v4, v16, v220
	v_cndmask_b32_e64 v16, v16, v4, s[38:39]
	v_mul_f32_e32 v5, v229, v5
	v_fmac_f32_e32 v5, v17, v221
	v_cndmask_b32_e64 v17, v17, v5, s[38:39]
	ds_swizzle_b32 v2, v10 offset:0x401f
	ds_swizzle_b32 v3, v11 offset:0x401f
	ds_swizzle_b32 v4, v12 offset:0x401f
	ds_swizzle_b32 v5, v13 offset:0x401f
	s_waitcnt lgkmcnt(0)
	v_mul_f32_e32 v2, v230, v2
	v_fmac_f32_e32 v2, v10, v222
	v_cndmask_b32_e64 v10, v10, v2, s[38:39]
	v_mul_f32_e32 v3, v231, v3
	v_fmac_f32_e32 v3, v11, v223
	v_cndmask_b32_e64 v11, v11, v3, s[38:39]
	v_mul_f32_e32 v4, v232, v4
	v_fmac_f32_e32 v4, v12, v224
	v_cndmask_b32_e64 v12, v12, v4, s[38:39]
	v_mul_f32_e32 v5, v233, v5
	v_fmac_f32_e32 v5, v13, v225
	v_cndmask_b32_e64 v13, v13, v5, s[38:39]
	v_pk_mul_f32 v[14:15], v[14:15], s[30:31] op_sel_hi:[1,0]
	v_pk_mul_f32 v[16:17], v[16:17], s[30:31] op_sel_hi:[1,0]
	v_pk_mul_f32 v[10:11], v[10:11], s[30:31] op_sel_hi:[1,0]
	v_pk_mul_f32 v[12:13], v[12:13], s[30:31] op_sel_hi:[1,0]
	v_cvt_pk_bf16_f32 v14, v14, v15
	v_cvt_pk_bf16_f32 v15, v16, v17
	v_cvt_pk_bf16_f32 v16, v10, v11
	v_cvt_pk_bf16_f32 v17, v12, v13
	s_mul_i32 s44, s66, 160
	s_add_u32 s100, s98, s44
	s_addc_u32 s101, s99, 0
	global_store_dwordx4 v200, v[26:29], s[100:101] nt
	s_add_u32 s100, s100, s67
	s_addc_u32 s101, s101, 0
	global_store_dwordx4 v200, v[18:21], s[100:101] nt
	ds_write_b128 v178, v[14:17]
	ds_write_b128 v178, v[6:9] offset:64
	ds_read_b128 v[10:13], v180
	ds_read_b128 v[2:5], v180 offset:1152
	s_waitcnt lgkmcnt(0)
	s_mul_i32 s44, s66, 176
	s_add_u32 s100, s98, s44
	s_addc_u32 s101, s99, 0
	global_store_dwordx4 v200, v[10:13], s[100:101] nt
	s_add_u32 s100, s100, s67
	s_addc_u32 s101, s101, 0
	global_store_dwordx4 v200, v[2:5], s[100:101] nt
	s_branch .Lipe_done
.Lipe_K:
	s_add_i32 s44, s19, 0
	s_and_b32 s44, s44, 0xfff
	v_or_b32_e32 v0, s44, v141
	v_lshlrev_b32_e32 v0, 6, v0
	global_load_dwordx4 v[154:157], v0, s[62:63]
	global_load_dwordx4 v[158:161], v0, s[62:63] offset:16
	global_load_dwordx4 v[162:165], v0, s[62:63] offset:32
	global_load_dwordx4 v[166:169], v0, s[62:63] offset:48
	s_add_i32 s44, s19, 16
	s_and_b32 s44, s44, 0xfff
	v_or_b32_e32 v0, s44, v141
	v_lshlrev_b32_e32 v0, 6, v0
	global_load_dwordx4 v[218:221], v0, s[62:63]
	global_load_dwordx4 v[222:225], v0, s[62:63] offset:16
	global_load_dwordx4 v[226:229], v0, s[62:63] offset:32
	global_load_dwordx4 v[230:233], v0, s[62:63] offset:48
	v_pk_mul_f32 v[118:119], v[118:119], v[152:153] op_sel_hi:[1,0]
	v_pk_mul_f32 v[120:121], v[120:121], v[152:153] op_sel_hi:[1,0]
	v_pk_mul_f32 v[114:115], v[114:115], v[152:153] op_sel_hi:[1,0]
	v_pk_mul_f32 v[116:117], v[116:117], v[152:153] op_sel_hi:[1,0]
	v_cvt_pk_bf16_f32 v118, v118, v119
	v_cvt_pk_bf16_f32 v119, v120, v121
	v_cvt_pk_bf16_f32 v120, v114, v115
	v_cvt_pk_bf16_f32 v121, v116, v117
	v_pk_mul_f32 v[126:127], v[126:127], v[152:153] op_sel_hi:[1,0]
	v_pk_mul_f32 v[128:129], v[128:129], v[152:153] op_sel_hi:[1,0]
	v_pk_mul_f32 v[122:123], v[122:123], v[152:153] op_sel_hi:[1,0]
	v_pk_mul_f32 v[124:125], v[124:125], v[152:153] op_sel_hi:[1,0]
	ds_swizzle_b32 v114, v126 offset:0x401f
	ds_swizzle_b32 v115, v127 offset:0x401f
	ds_swizzle_b32 v116, v128 offset:0x401f
	ds_swizzle_b32 v117, v129 offset:0x401f
	s_waitcnt vmcnt(4)
	v_xor_b32_e32 v162, v201, v162
	v_xor_b32_e32 v163, v201, v163
	v_xor_b32_e32 v164, v201, v164
	v_xor_b32_e32 v165, v201, v165
	v_xor_b32_e32 v166, v201, v166
	v_xor_b32_e32 v167, v201, v167
	v_xor_b32_e32 v168, v201, v168
	v_xor_b32_e32 v169, v201, v169
	s_waitcnt lgkmcnt(0)
	v_mul_f32_e32 v114, v162, v114
	v_fmac_f32_e32 v114, v126, v154
	v_cndmask_b32_e64 v126, v126, v114, s[38:39]
	v_mul_f32_e32 v115, v163, v115
	v_fmac_f32_e32 v115, v127, v155
	v_cndmask_b32_e64 v127, v127, v115, s[38:39]
	v_mul_f32_e32 v116, v164, v116
	v_fmac_f32_e32 v116, v128, v156
	v_cndmask_b32_e64 v128, v128, v116, s[38:39]
	v_mul_f32_e32 v117, v165, v117
	v_fmac_f32_e32 v117, v129, v157
	v_cndmask_b32_e64 v129, v129, v117, s[38:39]
	ds_swizzle_b32 v114, v122 offset:0x401f
	ds_swizzle_b32 v115, v123 offset:0x401f
	ds_swizzle_b32 v116, v124 offset:0x401f
	ds_swizzle_b32 v117, v125 offset:0x401f
	s_waitcnt lgkmcnt(0)
	v_mul_f32_e32 v114, v166, v114
	v_fmac_f32_e32 v114, v122, v158
	v_cndmask_b32_e64 v122, v122, v114, s[38:39]
	v_mul_f32_e32 v115, v167, v115
	v_fmac_f32_e32 v115, v123, v159
	v_cndmask_b32_e64 v123, v123, v115, s[38:39]
	v_mul_f32_e32 v116, v168, v116
	v_fmac_f32_e32 v116, v124, v160
	v_cndmask_b32_e64 v124, v124, v116, s[38:39]
	v_mul_f32_e32 v117, v169, v117
	v_fmac_f32_e32 v117, v125, v161
	v_cndmask_b32_e64 v125, v125, v117, s[38:39]
	v_cvt_pk_bf16_f32 v126, v126, v127
	v_cvt_pk_bf16_f32 v127, v128, v129
	v_cvt_pk_bf16_f32 v128, v122, v123
	v_cvt_pk_bf16_f32 v129, v124, v125
	ds_write_b128 v178, v[126:129]
	ds_write_b128 v178, v[118:121] offset:64
	ds_read_b128 v[122:125], v180
	ds_read_b128 v[114:117], v180 offset:1152
	s_add_i32 s44, s19, 32
	s_and_b32 s44, s44, 0xfff
	v_or_b32_e32 v0, s44, v141
	v_lshlrev_b32_e32 v0, 6, v0
	global_load_dwordx4 v[154:157], v0, s[62:63]
	global_load_dwordx4 v[158:161], v0, s[62:63] offset:16
	global_load_dwordx4 v[162:165], v0, s[62:63] offset:32
	global_load_dwordx4 v[166:169], v0, s[62:63] offset:48
	v_pk_mul_f32 v[102:103], v[102:103], v[152:153] op_sel:[0,1]
	v_pk_mul_f32 v[104:105], v[104:105], v[152:153] op_sel:[0,1]
	v_pk_mul_f32 v[98:99], v[98:99], v[152:153] op_sel:[0,1]
	v_pk_mul_f32 v[100:101], v[100:101], v[152:153] op_sel:[0,1]
	v_cvt_pk_bf16_f32 v102, v102, v103
	v_cvt_pk_bf16_f32 v103, v104, v105
	v_cvt_pk_bf16_f32 v104, v98, v99
	v_cvt_pk_bf16_f32 v105, v100, v101
	v_pk_mul_f32 v[110:111], v[110:111], v[152:153] op_sel:[0,1]
	v_pk_mul_f32 v[112:113], v[112:113], v[152:153] op_sel:[0,1]
	v_pk_mul_f32 v[106:107], v[106:107], v[152:153] op_sel:[0,1]
	v_pk_mul_f32 v[108:109], v[108:109], v[152:153] op_sel:[0,1]
	ds_swizzle_b32 v98, v110 offset:0x401f
	ds_swizzle_b32 v99, v111 offset:0x401f
	ds_swizzle_b32 v100, v112 offset:0x401f
	ds_swizzle_b32 v101, v113 offset:0x401f
	s_waitcnt vmcnt(4)
;     __device__ __forceinline__ void operator()(const f32x4 (&acc)[2][2][4][2], const Unit& u, int wr, int wc, int fr, int fq, PG8_LAS float* stash, int par, PG8_LAS unsigned char* stg, const Unit& un) const {
;     ...
;                     for (int i = 0; i < 4; ++i) { v[i] = acc[ai][bj][m][0][i] * rs; v[4 + i] = acc[ai][bj][m][1][i] * rs; }
;                     if (kind <= 1 && bj == 0) {
;                         const f32x4 c0 = *(const f32x4*)(cs + pos * 16), c1 = *(const f32x4*)(cs + pos * 16 + 4), s0 = *(const f32x4*)(cs + pos * 16 + 8), s1 = *(const f32x4*)(cs + pos * 16 + 12);
; #pragma unroll
;                         for (int i = 0; i < 8; ++i) {
;                             const float c = i < 4 ? c0[i & 3] : c1[i & 3], s = i < 4 ? s0[i & 3] : s1[i & 3];
;                             const float pr = peer_x16(v[i], fq);
;                             const float r = (fq == 0) ? (v[i] * c - pr * s) : (v[i] * c + pr * s);
;                             v[i] = (fq < 2) ? r : v[i];
;                         }
;                     }
;                     if (kind == 0) {
; #pragma unroll
;                         for (int i = 0; i < 8; ++i) v[i] *= C2Q;
;                     }
;                     { u32x4 w; w.x = cvt_pk_bf16(v[0], v[1]); w.y = cvt_pk_bf16(v[2], v[3]); w.z = cvt_pk_bf16(v[4], v[5]); w.w = cvt_pk_bf16(v[6], v[7]);
;                       *(PG8_LAS u32x4*)(stg + fr * 144 + fq * 16 + bj * 64) = w; }
;                 }
;                 {
;                     int kind;
;                     if (odd) kind = (u.pn < 6) ? 0 : (u.pn == 6 ? 1 : 2);
;                     else     kind = (u.pn < 2) ? 0 : (u.pn == 2 ? (wc < 2 ? 1 : 2) : 3);
; #pragma unroll
;                     for (int i = 0; i < 2; ++i) { const int c = fq * 16 + fr + 64 * i, rr = c >> 3, pc = c & 7;
;                         const u32x4 w = *(const PG8_LAS u32x4*)(stg + rr * 144 + pc * 16);
;                         const int rowc = row - fr + rr, posc = rowc & 4095;
;                         if (kind == 1 || kind == 2) {
;                             bf16_t* dst = (kind == 1) ? kd : vt;
;                             if (odd) *(u32x4*)(dst + (size_t)(b * 4 + wc) * (4096 * 64) + (size_t)((posc & 15) * 256 + (posc >> 4)) * 64 + pc * 8) = w;
;                             else     *(u32x4*)(dst + (size_t)(b * 2 + (wc & 1)) * (4096 * 64) + (size_t)posc * 64 + pc * 8) = w;
	v_xor_b32_e32 v226, v201, v226
	v_xor_b32_e32 v227, v201, v227
	v_xor_b32_e32 v228, v201, v228
	v_xor_b32_e32 v229, v201, v229
	v_xor_b32_e32 v230, v201, v230
	v_xor_b32_e32 v231, v201, v231
	v_xor_b32_e32 v232, v201, v232
	v_xor_b32_e32 v233, v201, v233
	s_waitcnt lgkmcnt(0)
	v_mul_f32_e32 v98, v226, v98
	v_fmac_f32_e32 v98, v110, v218
	v_cndmask_b32_e64 v110, v110, v98, s[38:39]
	v_mul_f32_e32 v99, v227, v99
	v_fmac_f32_e32 v99, v111, v219
	v_cndmask_b32_e64 v111, v111, v99, s[38:39]
	v_mul_f32_e32 v100, v228, v100
	v_fmac_f32_e32 v100, v112, v220
	v_cndmask_b32_e64 v112, v112, v100, s[38:39]
	v_mul_f32_e32 v101, v229, v101
	v_fmac_f32_e32 v101, v113, v221
	v_cndmask_b32_e64 v113, v113, v101, s[38:39]
	ds_swizzle_b32 v98, v106 offset:0x401f
	ds_swizzle_b32 v99, v107 offset:0x401f
	ds_swizzle_b32 v100, v108 offset:0x401f
	ds_swizzle_b32 v101, v109 offset:0x401f
	s_waitcnt lgkmcnt(0)
	v_mul_f32_e32 v98, v230, v98
	v_fmac_f32_e32 v98, v106, v222
	v_cndmask_b32_e64 v106, v106, v98, s[38:39]
	v_mul_f32_e32 v99, v231, v99
	v_fmac_f32_e32 v99, v107, v223
	v_cndmask_b32_e64 v107, v107, v99, s[38:39]
	v_mul_f32_e32 v100, v232, v100
	v_fmac_f32_e32 v100, v108, v224
	v_cndmask_b32_e64 v108, v108, v100, s[38:39]
	v_mul_f32_e32 v101, v233, v101
	v_fmac_f32_e32 v101, v109, v225
	v_cndmask_b32_e64 v109, v109, v101, s[38:39]
	v_cvt_pk_bf16_f32 v110, v110, v111
	v_cvt_pk_bf16_f32 v111, v112, v113
	v_cvt_pk_bf16_f32 v112, v106, v107
	v_cvt_pk_bf16_f32 v113, v108, v109
	s_mov_b32 s100, s98
	s_mov_b32 s101, s99
	global_store_dwordx4 v200, v[122:125], s[100:101] nt
	s_add_u32 s100, s100, s67
	s_addc_u32 s101, s101, 0
	global_store_dwordx4 v200, v[114:117], s[100:101] nt
	ds_write_b128 v178, v[110:113]
	ds_write_b128 v178, v[102:105] offset:64
	ds_read_b128 v[106:109], v180
	ds_read_b128 v[98:101], v180 offset:1152
	s_add_i32 s44, s19, 48
	s_and_b32 s44, s44, 0xfff
	v_or_b32_e32 v0, s44, v141
	v_lshlrev_b32_e32 v0, 6, v0
	global_load_dwordx4 v[218:221], v0, s[62:63]
	global_load_dwordx4 v[222:225], v0, s[62:63] offset:16
	global_load_dwordx4 v[226:229], v0, s[62:63] offset:32
	global_load_dwordx4 v[230:233], v0, s[62:63] offset:48
	v_pk_mul_f32 v[86:87], v[86:87], v[150:151] op_sel_hi:[1,0]
	v_pk_mul_f32 v[88:89], v[88:89], v[150:151] op_sel_hi:[1,0]
	v_pk_mul_f32 v[82:83], v[82:83], v[150:151] op_sel_hi:[1,0]
	v_pk_mul_f32 v[84:85], v[84:85], v[150:151] op_sel_hi:[1,0]
	v_cvt_pk_bf16_f32 v86, v86, v87
	v_cvt_pk_bf16_f32 v87, v88, v89
	v_cvt_pk_bf16_f32 v88, v82, v83
	v_cvt_pk_bf16_f32 v89, v84, v85
	v_pk_mul_f32 v[94:95], v[94:95], v[150:151] op_sel_hi:[1,0]
	v_pk_mul_f32 v[96:97], v[96:97], v[150:151] op_sel_hi:[1,0]
	v_pk_mul_f32 v[90:91], v[90:91], v[150:151] op_sel_hi:[1,0]
	v_pk_mul_f32 v[92:93], v[92:93], v[150:151] op_sel_hi:[1,0]
	ds_swizzle_b32 v82, v94 offset:0x401f
	ds_swizzle_b32 v83, v95 offset:0x401f
	ds_swizzle_b32 v84, v96 offset:0x401f
	ds_swizzle_b32 v85, v97 offset:0x401f
	s_waitcnt vmcnt(6)
	v_xor_b32_e32 v162, v201, v162
	v_xor_b32_e32 v163, v201, v163
	v_xor_b32_e32 v164, v201, v164
	v_xor_b32_e32 v165, v201, v165
	v_xor_b32_e32 v166, v201, v166
	v_xor_b32_e32 v167, v201, v167
	v_xor_b32_e32 v168, v201, v168
	v_xor_b32_e32 v169, v201, v169
	s_waitcnt lgkmcnt(0)
	v_mul_f32_e32 v82, v162, v82
	v_fmac_f32_e32 v82, v94, v154
	v_cndmask_b32_e64 v94, v94, v82, s[38:39]
	v_mul_f32_e32 v83, v163, v83
	v_fmac_f32_e32 v83, v95, v155
	v_cndmask_b32_e64 v95, v95, v83, s[38:39]
	v_mul_f32_e32 v84, v164, v84
	v_fmac_f32_e32 v84, v96, v156
	v_cndmask_b32_e64 v96, v96, v84, s[38:39]
	v_mul_f32_e32 v85, v165, v85
	v_fmac_f32_e32 v85, v97, v157
	v_cndmask_b32_e64 v97, v97, v85, s[38:39]
	ds_swizzle_b32 v82, v90 offset:0x401f
	ds_swizzle_b32 v83, v91 offset:0x401f
	ds_swizzle_b32 v84, v92 offset:0x401f
	ds_swizzle_b32 v85, v93 offset:0x401f
	s_waitcnt lgkmcnt(0)
	v_mul_f32_e32 v82, v166, v82
	v_fmac_f32_e32 v82, v90, v158
	v_cndmask_b32_e64 v90, v90, v82, s[38:39]
	v_mul_f32_e32 v83, v167, v83
	v_fmac_f32_e32 v83, v91, v159
	v_cndmask_b32_e64 v91, v91, v83, s[38:39]
	v_mul_f32_e32 v84, v168, v84
	v_fmac_f32_e32 v84, v92, v160
	v_cndmask_b32_e64 v92, v92, v84, s[38:39]
	v_mul_f32_e32 v85, v169, v85
	v_fmac_f32_e32 v85, v93, v161
	v_cndmask_b32_e64 v93, v93, v85, s[38:39]
	v_cvt_pk_bf16_f32 v94, v94, v95
	v_cvt_pk_bf16_f32 v95, v96, v97
	v_cvt_pk_bf16_f32 v96, v90, v91
	v_cvt_pk_bf16_f32 v97, v92, v93
	s_mul_i32 s44, s66, 16
	s_add_u32 s100, s98, s44
	s_addc_u32 s101, s99, 0
	global_store_dwordx4 v200, v[106:109], s[100:101] nt
	s_add_u32 s100, s100, s67
	s_addc_u32 s101, s101, 0
	global_store_dwordx4 v200, v[98:101], s[100:101] nt
	ds_write_b128 v178, v[94:97]
	ds_write_b128 v178, v[86:89] offset:64
	ds_read_b128 v[90:93], v180
	ds_read_b128 v[82:85], v180 offset:1152
	s_add_i32 s44, s19, 128
	s_and_b32 s44, s44, 0xfff
	v_or_b32_e32 v0, s44, v141
	v_lshlrev_b32_e32 v0, 6, v0
	global_load_dwordx4 v[154:157], v0, s[62:63]
	global_load_dwordx4 v[158:161], v0, s[62:63] offset:16
	global_load_dwordx4 v[162:165], v0, s[62:63] offset:32
	global_load_dwordx4 v[166:169], v0, s[62:63] offset:48
	v_pk_mul_f32 v[70:71], v[70:71], v[150:151] op_sel:[0,1]
	v_pk_mul_f32 v[72:73], v[72:73], v[150:151] op_sel:[0,1]
	v_pk_mul_f32 v[66:67], v[66:67], v[150:151] op_sel:[0,1]
	v_pk_mul_f32 v[68:69], v[68:69], v[150:151] op_sel:[0,1]
	v_cvt_pk_bf16_f32 v70, v70, v71
	v_cvt_pk_bf16_f32 v71, v72, v73
	v_cvt_pk_bf16_f32 v72, v66, v67
	v_cvt_pk_bf16_f32 v73, v68, v69
	v_pk_mul_f32 v[78:79], v[78:79], v[150:151] op_sel:[0,1]
	v_pk_mul_f32 v[80:81], v[80:81], v[150:151] op_sel:[0,1]
	v_pk_mul_f32 v[74:75], v[74:75], v[150:151] op_sel:[0,1]
	v_pk_mul_f32 v[76:77], v[76:77], v[150:151] op_sel:[0,1]
	ds_swizzle_b32 v66, v78 offset:0x401f
	ds_swizzle_b32 v67, v79 offset:0x401f
	ds_swizzle_b32 v68, v80 offset:0x401f
	ds_swizzle_b32 v69, v81 offset:0x401f
	s_waitcnt vmcnt(6)
;     __device__ __forceinline__ void operator()(const f32x4 (&acc)[2][2][4][2], const Unit& u, int wr, int wc, int fr, int fq, PG8_LAS float* stash, int par, PG8_LAS unsigned char* stg, const Unit& un) const {
;     ...
;                     for (int i = 0; i < 4; ++i) { v[i] = acc[ai][bj][m][0][i] * rs; v[4 + i] = acc[ai][bj][m][1][i] * rs; }
;                     if (kind <= 1 && bj == 0) {
;                         const f32x4 c0 = *(const f32x4*)(cs + pos * 16), c1 = *(const f32x4*)(cs + pos * 16 + 4), s0 = *(const f32x4*)(cs + pos * 16 + 8), s1 = *(const f32x4*)(cs + pos * 16 + 12);
; #pragma unroll
;                         for (int i = 0; i < 8; ++i) {
;                             const float c = i < 4 ? c0[i & 3] : c1[i & 3], s = i < 4 ? s0[i & 3] : s1[i & 3];
;                             const float pr = peer_x16(v[i], fq);
;                             const float r = (fq == 0) ? (v[i] * c - pr * s) : (v[i] * c + pr * s);
;                             v[i] = (fq < 2) ? r : v[i];
;                         }
;                     }
;                     if (kind == 0) {
; #pragma unroll
;                         for (int i = 0; i < 8; ++i) v[i] *= C2Q;
;                     }
;                     { u32x4 w; w.x = cvt_pk_bf16(v[0], v[1]); w.y = cvt_pk_bf16(v[2], v[3]); w.z = cvt_pk_bf16(v[4], v[5]); w.w = cvt_pk_bf16(v[6], v[7]);
;                       *(PG8_LAS u32x4*)(stg + fr * 144 + fq * 16 + bj * 64) = w; }
;                 }
;                 {
;                     int kind;
;                     if (odd) kind = (u.pn < 6) ? 0 : (u.pn == 6 ? 1 : 2);
;                     else     kind = (u.pn < 2) ? 0 : (u.pn == 2 ? (wc < 2 ? 1 : 2) : 3);
; #pragma unroll
;                     for (int i = 0; i < 2; ++i) { const int c = fq * 16 + fr + 64 * i, rr = c >> 3, pc = c & 7;
;                         const u32x4 w = *(const PG8_LAS u32x4*)(stg + rr * 144 + pc * 16);
;                         const int rowc = row - fr + rr, posc = rowc & 4095;
;                         if (kind == 1 || kind == 2) {
;                             bf16_t* dst = (kind == 1) ? kd : vt;
;                             if (odd) *(u32x4*)(dst + (size_t)(b * 4 + wc) * (4096 * 64) + (size_t)((posc & 15) * 256 + (posc >> 4)) * 64 + pc * 8) = w;
;                             else     *(u32x4*)(dst + (size_t)(b * 2 + (wc & 1)) * (4096 * 64) + (size_t)posc * 64 + pc * 8) = w;
	v_xor_b32_e32 v226, v201, v226
	v_xor_b32_e32 v227, v201, v227
	v_xor_b32_e32 v228, v201, v228
	v_xor_b32_e32 v229, v201, v229
	v_xor_b32_e32 v230, v201, v230
	v_xor_b32_e32 v231, v201, v231
	v_xor_b32_e32 v232, v201, v232
	v_xor_b32_e32 v233, v201, v233
	s_waitcnt lgkmcnt(0)
	v_mul_f32_e32 v66, v226, v66
	v_fmac_f32_e32 v66, v78, v218
	v_cndmask_b32_e64 v78, v78, v66, s[38:39]
	v_mul_f32_e32 v67, v227, v67
	v_fmac_f32_e32 v67, v79, v219
	v_cndmask_b32_e64 v79, v79, v67, s[38:39]
	v_mul_f32_e32 v68, v228, v68
	v_fmac_f32_e32 v68, v80, v220
	v_cndmask_b32_e64 v80, v80, v68, s[38:39]
	v_mul_f32_e32 v69, v229, v69
	v_fmac_f32_e32 v69, v81, v221
	v_cndmask_b32_e64 v81, v81, v69, s[38:39]
	ds_swizzle_b32 v66, v74 offset:0x401f
	ds_swizzle_b32 v67, v75 offset:0x401f
	ds_swizzle_b32 v68, v76 offset:0x401f
	ds_swizzle_b32 v69, v77 offset:0x401f
	s_waitcnt lgkmcnt(0)
	v_mul_f32_e32 v66, v230, v66
	v_fmac_f32_e32 v66, v74, v222
	v_cndmask_b32_e64 v74, v74, v66, s[38:39]
	v_mul_f32_e32 v67, v231, v67
	v_fmac_f32_e32 v67, v75, v223
	v_cndmask_b32_e64 v75, v75, v67, s[38:39]
	v_mul_f32_e32 v68, v232, v68
	v_fmac_f32_e32 v68, v76, v224
	v_cndmask_b32_e64 v76, v76, v68, s[38:39]
	v_mul_f32_e32 v69, v233, v69
	v_fmac_f32_e32 v69, v77, v225
	v_cndmask_b32_e64 v77, v77, v69, s[38:39]
	v_cvt_pk_bf16_f32 v78, v78, v79
	v_cvt_pk_bf16_f32 v79, v80, v81
	v_cvt_pk_bf16_f32 v80, v74, v75
	v_cvt_pk_bf16_f32 v81, v76, v77
	s_mul_i32 s44, s66, 32
	s_add_u32 s100, s98, s44
	s_addc_u32 s101, s99, 0
	global_store_dwordx4 v200, v[90:93], s[100:101] nt
	s_add_u32 s100, s100, s67
	s_addc_u32 s101, s101, 0
	global_store_dwordx4 v200, v[82:85], s[100:101] nt
	ds_write_b128 v178, v[78:81]
	ds_write_b128 v178, v[70:73] offset:64
	ds_read_b128 v[74:77], v180
	ds_read_b128 v[66:69], v180 offset:1152
	s_add_i32 s44, s19, 144
	s_and_b32 s44, s44, 0xfff
	v_or_b32_e32 v0, s44, v141
	v_lshlrev_b32_e32 v0, 6, v0
	global_load_dwordx4 v[218:221], v0, s[62:63]
	global_load_dwordx4 v[222:225], v0, s[62:63] offset:16
	global_load_dwordx4 v[226:229], v0, s[62:63] offset:32
	global_load_dwordx4 v[230:233], v0, s[62:63] offset:48
	v_pk_mul_f32 v[54:55], v[54:55], v[148:149] op_sel_hi:[1,0]
	v_pk_mul_f32 v[56:57], v[56:57], v[148:149] op_sel_hi:[1,0]
	v_pk_mul_f32 v[50:51], v[50:51], v[148:149] op_sel_hi:[1,0]
	v_pk_mul_f32 v[52:53], v[52:53], v[148:149] op_sel_hi:[1,0]
	v_cvt_pk_bf16_f32 v54, v54, v55
	v_cvt_pk_bf16_f32 v55, v56, v57
	v_cvt_pk_bf16_f32 v56, v50, v51
	v_cvt_pk_bf16_f32 v57, v52, v53
	v_pk_mul_f32 v[62:63], v[62:63], v[148:149] op_sel_hi:[1,0]
	v_pk_mul_f32 v[64:65], v[64:65], v[148:149] op_sel_hi:[1,0]
	v_pk_mul_f32 v[58:59], v[58:59], v[148:149] op_sel_hi:[1,0]
	v_pk_mul_f32 v[60:61], v[60:61], v[148:149] op_sel_hi:[1,0]
	ds_swizzle_b32 v50, v62 offset:0x401f
	ds_swizzle_b32 v51, v63 offset:0x401f
	ds_swizzle_b32 v52, v64 offset:0x401f
	ds_swizzle_b32 v53, v65 offset:0x401f
	s_waitcnt vmcnt(6)
	v_xor_b32_e32 v162, v201, v162
	v_xor_b32_e32 v163, v201, v163
	v_xor_b32_e32 v164, v201, v164
	v_xor_b32_e32 v165, v201, v165
	v_xor_b32_e32 v166, v201, v166
	v_xor_b32_e32 v167, v201, v167
	v_xor_b32_e32 v168, v201, v168
	v_xor_b32_e32 v169, v201, v169
	s_waitcnt lgkmcnt(0)
	v_mul_f32_e32 v50, v162, v50
	v_fmac_f32_e32 v50, v62, v154
	v_cndmask_b32_e64 v62, v62, v50, s[38:39]
	v_mul_f32_e32 v51, v163, v51
	v_fmac_f32_e32 v51, v63, v155
	v_cndmask_b32_e64 v63, v63, v51, s[38:39]
	v_mul_f32_e32 v52, v164, v52
	v_fmac_f32_e32 v52, v64, v156
	v_cndmask_b32_e64 v64, v64, v52, s[38:39]
	v_mul_f32_e32 v53, v165, v53
	v_fmac_f32_e32 v53, v65, v157
	v_cndmask_b32_e64 v65, v65, v53, s[38:39]
	ds_swizzle_b32 v50, v58 offset:0x401f
	ds_swizzle_b32 v51, v59 offset:0x401f
	ds_swizzle_b32 v52, v60 offset:0x401f
	ds_swizzle_b32 v53, v61 offset:0x401f
	s_waitcnt lgkmcnt(0)
	v_mul_f32_e32 v50, v166, v50
	v_fmac_f32_e32 v50, v58, v158
	v_cndmask_b32_e64 v58, v58, v50, s[38:39]
	v_mul_f32_e32 v51, v167, v51
	v_fmac_f32_e32 v51, v59, v159
	v_cndmask_b32_e64 v59, v59, v51, s[38:39]
	v_mul_f32_e32 v52, v168, v52
	v_fmac_f32_e32 v52, v60, v160
	v_cndmask_b32_e64 v60, v60, v52, s[38:39]
	v_mul_f32_e32 v53, v169, v53
	v_fmac_f32_e32 v53, v61, v161
	v_cndmask_b32_e64 v61, v61, v53, s[38:39]
	v_cvt_pk_bf16_f32 v62, v62, v63
	v_cvt_pk_bf16_f32 v63, v64, v65
	v_cvt_pk_bf16_f32 v64, v58, v59
	v_cvt_pk_bf16_f32 v65, v60, v61
	s_mul_i32 s44, s66, 48
	s_add_u32 s100, s98, s44
	s_addc_u32 s101, s99, 0
	global_store_dwordx4 v200, v[74:77], s[100:101] nt
	s_add_u32 s100, s100, s67
	s_addc_u32 s101, s101, 0
	global_store_dwordx4 v200, v[66:69], s[100:101] nt
	ds_write_b128 v178, v[62:65]
	ds_write_b128 v178, v[54:57] offset:64
	ds_read_b128 v[58:61], v180
	ds_read_b128 v[50:53], v180 offset:1152
	s_add_i32 s44, s19, 160
	s_and_b32 s44, s44, 0xfff
	v_or_b32_e32 v0, s44, v141
	v_lshlrev_b32_e32 v0, 6, v0
	global_load_dwordx4 v[154:157], v0, s[62:63]
	global_load_dwordx4 v[158:161], v0, s[62:63] offset:16
	global_load_dwordx4 v[162:165], v0, s[62:63] offset:32
	global_load_dwordx4 v[166:169], v0, s[62:63] offset:48
	v_pk_mul_f32 v[38:39], v[38:39], v[148:149] op_sel:[0,1]
	v_pk_mul_f32 v[40:41], v[40:41], v[148:149] op_sel:[0,1]
	v_pk_mul_f32 v[34:35], v[34:35], v[148:149] op_sel:[0,1]
	v_pk_mul_f32 v[36:37], v[36:37], v[148:149] op_sel:[0,1]
	v_cvt_pk_bf16_f32 v38, v38, v39
	v_cvt_pk_bf16_f32 v39, v40, v41
	v_cvt_pk_bf16_f32 v40, v34, v35
	v_cvt_pk_bf16_f32 v41, v36, v37
	v_pk_mul_f32 v[46:47], v[46:47], v[148:149] op_sel:[0,1]
	v_pk_mul_f32 v[48:49], v[48:49], v[148:149] op_sel:[0,1]
	v_pk_mul_f32 v[42:43], v[42:43], v[148:149] op_sel:[0,1]
	v_pk_mul_f32 v[44:45], v[44:45], v[148:149] op_sel:[0,1]
	ds_swizzle_b32 v34, v46 offset:0x401f
	ds_swizzle_b32 v35, v47 offset:0x401f
	ds_swizzle_b32 v36, v48 offset:0x401f
	ds_swizzle_b32 v37, v49 offset:0x401f
	s_waitcnt vmcnt(6)
;     __device__ __forceinline__ void operator()(const f32x4 (&acc)[2][2][4][2], const Unit& u, int wr, int wc, int fr, int fq, PG8_LAS float* stash, int par, PG8_LAS unsigned char* stg, const Unit& un) const {
;     ...
;                     for (int i = 0; i < 4; ++i) { v[i] = acc[ai][bj][m][0][i] * rs; v[4 + i] = acc[ai][bj][m][1][i] * rs; }
;                     if (kind <= 1 && bj == 0) {
;                         const f32x4 c0 = *(const f32x4*)(cs + pos * 16), c1 = *(const f32x4*)(cs + pos * 16 + 4), s0 = *(const f32x4*)(cs + pos * 16 + 8), s1 = *(const f32x4*)(cs + pos * 16 + 12);
; #pragma unroll
;                         for (int i = 0; i < 8; ++i) {
;                             const float c = i < 4 ? c0[i & 3] : c1[i & 3], s = i < 4 ? s0[i & 3] : s1[i & 3];
;                             const float pr = peer_x16(v[i], fq);
;                             const float r = (fq == 0) ? (v[i] * c - pr * s) : (v[i] * c + pr * s);
;                             v[i] = (fq < 2) ? r : v[i];
;                         }
;                     }
;                     if (kind == 0) {
; #pragma unroll
;                         for (int i = 0; i < 8; ++i) v[i] *= C2Q;
;                     }
;                     { u32x4 w; w.x = cvt_pk_bf16(v[0], v[1]); w.y = cvt_pk_bf16(v[2], v[3]); w.z = cvt_pk_bf16(v[4], v[5]); w.w = cvt_pk_bf16(v[6], v[7]);
;                       *(PG8_LAS u32x4*)(stg + fr * 144 + fq * 16 + bj * 64) = w; }
;                 }
;                 {
;                     int kind;
;                     if (odd) kind = (u.pn < 6) ? 0 : (u.pn == 6 ? 1 : 2);
;                     else     kind = (u.pn < 2) ? 0 : (u.pn == 2 ? (wc < 2 ? 1 : 2) : 3);
; #pragma unroll
;                     for (int i = 0; i < 2; ++i) { const int c = fq * 16 + fr + 64 * i, rr = c >> 3, pc = c & 7;
;                         const u32x4 w = *(const PG8_LAS u32x4*)(stg + rr * 144 + pc * 16);
;                         const int rowc = row - fr + rr, posc = rowc & 4095;
;                         if (kind == 1 || kind == 2) {
;                             bf16_t* dst = (kind == 1) ? kd : vt;
;                             if (odd) *(u32x4*)(dst + (size_t)(b * 4 + wc) * (4096 * 64) + (size_t)((posc & 15) * 256 + (posc >> 4)) * 64 + pc * 8) = w;
;                             else     *(u32x4*)(dst + (size_t)(b * 2 + (wc & 1)) * (4096 * 64) + (size_t)posc * 64 + pc * 8) = w;
	v_xor_b32_e32 v226, v201, v226
	v_xor_b32_e32 v227, v201, v227
	v_xor_b32_e32 v228, v201, v228
	v_xor_b32_e32 v229, v201, v229
	v_xor_b32_e32 v230, v201, v230
	v_xor_b32_e32 v231, v201, v231
	v_xor_b32_e32 v232, v201, v232
	v_xor_b32_e32 v233, v201, v233
	s_waitcnt lgkmcnt(0)
	v_mul_f32_e32 v34, v226, v34
	v_fmac_f32_e32 v34, v46, v218
	v_cndmask_b32_e64 v46, v46, v34, s[38:39]
	v_mul_f32_e32 v35, v227, v35
	v_fmac_f32_e32 v35, v47, v219
	v_cndmask_b32_e64 v47, v47, v35, s[38:39]
	v_mul_f32_e32 v36, v228, v36
	v_fmac_f32_e32 v36, v48, v220
	v_cndmask_b32_e64 v48, v48, v36, s[38:39]
	v_mul_f32_e32 v37, v229, v37
	v_fmac_f32_e32 v37, v49, v221
	v_cndmask_b32_e64 v49, v49, v37, s[38:39]
	ds_swizzle_b32 v34, v42 offset:0x401f
	ds_swizzle_b32 v35, v43 offset:0x401f
	ds_swizzle_b32 v36, v44 offset:0x401f
	ds_swizzle_b32 v37, v45 offset:0x401f
	s_waitcnt lgkmcnt(0)
	v_mul_f32_e32 v34, v230, v34
	v_fmac_f32_e32 v34, v42, v222
	v_cndmask_b32_e64 v42, v42, v34, s[38:39]
	v_mul_f32_e32 v35, v231, v35
	v_fmac_f32_e32 v35, v43, v223
	v_cndmask_b32_e64 v43, v43, v35, s[38:39]
	v_mul_f32_e32 v36, v232, v36
	v_fmac_f32_e32 v36, v44, v224
	v_cndmask_b32_e64 v44, v44, v36, s[38:39]
	v_mul_f32_e32 v37, v233, v37
	v_fmac_f32_e32 v37, v45, v225
	v_cndmask_b32_e64 v45, v45, v37, s[38:39]
	v_cvt_pk_bf16_f32 v46, v46, v47
	v_cvt_pk_bf16_f32 v47, v48, v49
	v_cvt_pk_bf16_f32 v48, v42, v43
	v_cvt_pk_bf16_f32 v49, v44, v45
	s_mul_i32 s44, s66, 128
	s_add_u32 s100, s98, s44
	s_addc_u32 s101, s99, 0
	global_store_dwordx4 v200, v[58:61], s[100:101] nt
	s_add_u32 s100, s100, s67
	s_addc_u32 s101, s101, 0
	global_store_dwordx4 v200, v[50:53], s[100:101] nt
	ds_write_b128 v178, v[46:49]
	ds_write_b128 v178, v[38:41] offset:64
	ds_read_b128 v[42:45], v180
	ds_read_b128 v[34:37], v180 offset:1152
	s_add_i32 s44, s19, 176
	s_and_b32 s44, s44, 0xfff
	v_or_b32_e32 v0, s44, v141
	v_lshlrev_b32_e32 v0, 6, v0
	global_load_dwordx4 v[218:221], v0, s[62:63]
	global_load_dwordx4 v[222:225], v0, s[62:63] offset:16
	global_load_dwordx4 v[226:229], v0, s[62:63] offset:32
	global_load_dwordx4 v[230:233], v0, s[62:63] offset:48
	v_pk_mul_f32 v[22:23], v[22:23], v[146:147] op_sel_hi:[1,0]
	v_pk_mul_f32 v[24:25], v[24:25], v[146:147] op_sel_hi:[1,0]
	v_pk_mul_f32 v[18:19], v[18:19], v[146:147] op_sel_hi:[1,0]
	v_pk_mul_f32 v[20:21], v[20:21], v[146:147] op_sel_hi:[1,0]
	v_cvt_pk_bf16_f32 v22, v22, v23
	v_cvt_pk_bf16_f32 v23, v24, v25
	v_cvt_pk_bf16_f32 v24, v18, v19
	v_cvt_pk_bf16_f32 v25, v20, v21
	v_pk_mul_f32 v[30:31], v[30:31], v[146:147] op_sel_hi:[1,0]
	v_pk_mul_f32 v[32:33], v[32:33], v[146:147] op_sel_hi:[1,0]
	v_pk_mul_f32 v[26:27], v[26:27], v[146:147] op_sel_hi:[1,0]
	v_pk_mul_f32 v[28:29], v[28:29], v[146:147] op_sel_hi:[1,0]
	ds_swizzle_b32 v18, v30 offset:0x401f
	ds_swizzle_b32 v19, v31 offset:0x401f
	ds_swizzle_b32 v20, v32 offset:0x401f
	ds_swizzle_b32 v21, v33 offset:0x401f
	s_waitcnt vmcnt(6)
	v_xor_b32_e32 v162, v201, v162
	v_xor_b32_e32 v163, v201, v163
	v_xor_b32_e32 v164, v201, v164
	v_xor_b32_e32 v165, v201, v165
	v_xor_b32_e32 v166, v201, v166
	v_xor_b32_e32 v167, v201, v167
	v_xor_b32_e32 v168, v201, v168
	v_xor_b32_e32 v169, v201, v169
	s_waitcnt lgkmcnt(0)
	v_mul_f32_e32 v18, v162, v18
	v_fmac_f32_e32 v18, v30, v154
	v_cndmask_b32_e64 v30, v30, v18, s[38:39]
	v_mul_f32_e32 v19, v163, v19
	v_fmac_f32_e32 v19, v31, v155
	v_cndmask_b32_e64 v31, v31, v19, s[38:39]
	v_mul_f32_e32 v20, v164, v20
	v_fmac_f32_e32 v20, v32, v156
	v_cndmask_b32_e64 v32, v32, v20, s[38:39]
	v_mul_f32_e32 v21, v165, v21
	v_fmac_f32_e32 v21, v33, v157
	v_cndmask_b32_e64 v33, v33, v21, s[38:39]
	ds_swizzle_b32 v18, v26 offset:0x401f
	ds_swizzle_b32 v19, v27 offset:0x401f
	ds_swizzle_b32 v20, v28 offset:0x401f
	ds_swizzle_b32 v21, v29 offset:0x401f
	s_waitcnt lgkmcnt(0)
	v_mul_f32_e32 v18, v166, v18
	v_fmac_f32_e32 v18, v26, v158
	v_cndmask_b32_e64 v26, v26, v18, s[38:39]
	v_mul_f32_e32 v19, v167, v19
	v_fmac_f32_e32 v19, v27, v159
	v_cndmask_b32_e64 v27, v27, v19, s[38:39]
	v_mul_f32_e32 v20, v168, v20
	v_fmac_f32_e32 v20, v28, v160
	v_cndmask_b32_e64 v28, v28, v20, s[38:39]
	v_mul_f32_e32 v21, v169, v21
	v_fmac_f32_e32 v21, v29, v161
	v_cndmask_b32_e64 v29, v29, v21, s[38:39]
	v_cvt_pk_bf16_f32 v30, v30, v31
	v_cvt_pk_bf16_f32 v31, v32, v33
	v_cvt_pk_bf16_f32 v32, v26, v27
	v_cvt_pk_bf16_f32 v33, v28, v29
	s_mul_i32 s44, s66, 144
	s_add_u32 s100, s98, s44
	s_addc_u32 s101, s99, 0
	global_store_dwordx4 v200, v[42:45], s[100:101] nt
	s_add_u32 s100, s100, s67
	s_addc_u32 s101, s101, 0
	global_store_dwordx4 v200, v[34:37], s[100:101] nt
	ds_write_b128 v178, v[30:33]
	ds_write_b128 v178, v[22:25] offset:64
	ds_read_b128 v[26:29], v180
	ds_read_b128 v[18:21], v180 offset:1152
	v_pk_mul_f32 v[6:7], v[6:7], v[146:147] op_sel:[0,1]
	v_pk_mul_f32 v[8:9], v[8:9], v[146:147] op_sel:[0,1]
	v_pk_mul_f32 v[2:3], v[2:3], v[146:147] op_sel:[0,1]
	v_pk_mul_f32 v[4:5], v[4:5], v[146:147] op_sel:[0,1]
	v_cvt_pk_bf16_f32 v6, v6, v7
	v_cvt_pk_bf16_f32 v7, v8, v9
	v_cvt_pk_bf16_f32 v8, v2, v3
	v_cvt_pk_bf16_f32 v9, v4, v5
	v_pk_mul_f32 v[14:15], v[14:15], v[146:147] op_sel:[0,1]
	v_pk_mul_f32 v[16:17], v[16:17], v[146:147] op_sel:[0,1]
	v_pk_mul_f32 v[10:11], v[10:11], v[146:147] op_sel:[0,1]
	v_pk_mul_f32 v[12:13], v[12:13], v[146:147] op_sel:[0,1]
	ds_swizzle_b32 v2, v14 offset:0x401f
	ds_swizzle_b32 v3, v15 offset:0x401f
	ds_swizzle_b32 v4, v16 offset:0x401f
	ds_swizzle_b32 v5, v17 offset:0x401f
	s_waitcnt vmcnt(2)
	v_xor_b32_e32 v226, v201, v226
	v_xor_b32_e32 v227, v201, v227
	v_xor_b32_e32 v228, v201, v228
	v_xor_b32_e32 v229, v201, v229
	v_xor_b32_e32 v230, v201, v230
	v_xor_b32_e32 v231, v201, v231
	v_xor_b32_e32 v232, v201, v232
	v_xor_b32_e32 v233, v201, v233
	s_waitcnt lgkmcnt(0)
;     __device__ __forceinline__ void operator()(const f32x4 (&acc)[2][2][4][2], const Unit& u, int wr, int wc, int fr, int fq, PG8_LAS float* stash, int par, PG8_LAS unsigned char* stg, const Unit& un) const {
;     ...
;                     for (int i = 0; i < 4; ++i) { v[i] = acc[ai][bj][m][0][i] * rs; v[4 + i] = acc[ai][bj][m][1][i] * rs; }
;                     if (kind <= 1 && bj == 0) {
;                         const f32x4 c0 = *(const f32x4*)(cs + pos * 16), c1 = *(const f32x4*)(cs + pos * 16 + 4), s0 = *(const f32x4*)(cs + pos * 16 + 8), s1 = *(const f32x4*)(cs + pos * 16 + 12);
; #pragma unroll
;                         for (int i = 0; i < 8; ++i) {
;                             const float c = i < 4 ? c0[i & 3] : c1[i & 3], s = i < 4 ? s0[i & 3] : s1[i & 3];
;                             const float pr = peer_x16(v[i], fq);
;                             const float r = (fq == 0) ? (v[i] * c - pr * s) : (v[i] * c + pr * s);
;                             v[i] = (fq < 2) ? r : v[i];
;                         }
;                     }
;                     if (kind == 0) {
; #pragma unroll
;                         for (int i = 0; i < 8; ++i) v[i] *= C2Q;
;                     }
;                     { u32x4 w; w.x = cvt_pk_bf16(v[0], v[1]); w.y = cvt_pk_bf16(v[2], v[3]); w.z = cvt_pk_bf16(v[4], v[5]); w.w = cvt_pk_bf16(v[6], v[7]);
;                       *(PG8_LAS u32x4*)(stg + fr * 144 + fq * 16 + bj * 64) = w; }
;                 }
;                 {
;                     int kind;
;                     if (odd) kind = (u.pn < 6) ? 0 : (u.pn == 6 ? 1 : 2);
;                     else     kind = (u.pn < 2) ? 0 : (u.pn == 2 ? (wc < 2 ? 1 : 2) : 3);
; #pragma unroll
;                     for (int i = 0; i < 2; ++i) { const int c = fq * 16 + fr + 64 * i, rr = c >> 3, pc = c & 7;
;                         const u32x4 w = *(const PG8_LAS u32x4*)(stg + rr * 144 + pc * 16);
;                         const int rowc = row - fr + rr, posc = rowc & 4095;
;                         if (kind == 1 || kind == 2) {
;                             bf16_t* dst = (kind == 1) ? kd : vt;
;                             if (odd) *(u32x4*)(dst + (size_t)(b * 4 + wc) * (4096 * 64) + (size_t)((posc & 15) * 256 + (posc >> 4)) * 64 + pc * 8) = w;
;                             else     *(u32x4*)(dst + (size_t)(b * 2 + (wc & 1)) * (4096 * 64) + (size_t)posc * 64 + pc * 8) = w;
	v_mul_f32_e32 v2, v226, v2
	v_fmac_f32_e32 v2, v14, v218
	v_cndmask_b32_e64 v14, v14, v2, s[38:39]
	v_mul_f32_e32 v3, v227, v3
	v_fmac_f32_e32 v3, v15, v219
	v_cndmask_b32_e64 v15, v15, v3, s[38:39]
	v_mul_f32_e32 v4, v228, v4
	v_fmac_f32_e32 v4, v16, v220
	v_cndmask_b32_e64 v16, v16, v4, s[38:39]
	v_mul_f32_e32 v5, v229, v5
	v_fmac_f32_e32 v5, v17, v221
	v_cndmask_b32_e64 v17, v17, v5, s[38:39]
	ds_swizzle_b32 v2, v10 offset:0x401f
	ds_swizzle_b32 v3, v11 offset:0x401f
	ds_swizzle_b32 v4, v12 offset:0x401f
	ds_swizzle_b32 v5, v13 offset:0x401f
	s_waitcnt lgkmcnt(0)
	v_mul_f32_e32 v2, v230, v2
	v_fmac_f32_e32 v2, v10, v222
	v_cndmask_b32_e64 v10, v10, v2, s[38:39]
	v_mul_f32_e32 v3, v231, v3
	v_fmac_f32_e32 v3, v11, v223
	v_cndmask_b32_e64 v11, v11, v3, s[38:39]
	v_mul_f32_e32 v4, v232, v4
	v_fmac_f32_e32 v4, v12, v224
	v_cndmask_b32_e64 v12, v12, v4, s[38:39]
	v_mul_f32_e32 v5, v233, v5
	v_fmac_f32_e32 v5, v13, v225
	v_cndmask_b32_e64 v13, v13, v5, s[38:39]
	v_cvt_pk_bf16_f32 v14, v14, v15
	v_cvt_pk_bf16_f32 v15, v16, v17
	v_cvt_pk_bf16_f32 v16, v10, v11
	v_cvt_pk_bf16_f32 v17, v12, v13
	s_mul_i32 s44, s66, 160
	s_add_u32 s100, s98, s44
	s_addc_u32 s101, s99, 0
	global_store_dwordx4 v200, v[26:29], s[100:101] nt
	s_add_u32 s100, s100, s67
	s_addc_u32 s101, s101, 0
	global_store_dwordx4 v200, v[18:21], s[100:101] nt
	ds_write_b128 v178, v[14:17]
	ds_write_b128 v178, v[6:9] offset:64
	ds_read_b128 v[10:13], v180
	ds_read_b128 v[2:5], v180 offset:1152
	s_waitcnt lgkmcnt(0)
	s_mul_i32 s44, s66, 176
	s_add_u32 s100, s98, s44
	s_addc_u32 s101, s99, 0
	global_store_dwordx4 v200, v[10:13], s[100:101] nt
	s_add_u32 s100, s100, s67
	s_addc_u32 s101, s101, 0
	global_store_dwordx4 v200, v[2:5], s[100:101] nt
	s_branch .Lipe_done
.Lipe_P:
	v_pk_mul_f32 v[118:119], v[118:119], v[152:153] op_sel_hi:[1,0]
	v_pk_mul_f32 v[120:121], v[120:121], v[152:153] op_sel_hi:[1,0]
	v_pk_mul_f32 v[114:115], v[114:115], v[152:153] op_sel_hi:[1,0]
	v_pk_mul_f32 v[116:117], v[116:117], v[152:153] op_sel_hi:[1,0]
	v_cvt_pk_bf16_f32 v118, v118, v119
	v_cvt_pk_bf16_f32 v119, v120, v121
	v_cvt_pk_bf16_f32 v120, v114, v115
	v_cvt_pk_bf16_f32 v121, v116, v117
	v_pk_mul_f32 v[126:127], v[126:127], v[152:153] op_sel_hi:[1,0]
	v_pk_mul_f32 v[128:129], v[128:129], v[152:153] op_sel_hi:[1,0]
	v_pk_mul_f32 v[122:123], v[122:123], v[152:153] op_sel_hi:[1,0]
	v_pk_mul_f32 v[124:125], v[124:125], v[152:153] op_sel_hi:[1,0]
	s_waitcnt lgkmcnt(0)
	v_cvt_pk_bf16_f32 v126, v126, v127
	v_cvt_pk_bf16_f32 v127, v128, v129
	v_cvt_pk_bf16_f32 v128, v122, v123
	v_cvt_pk_bf16_f32 v129, v124, v125
	ds_write_b128 v178, v[126:129]
	ds_write_b128 v178, v[118:121] offset:64
	ds_read_b128 v[122:125], v180
	ds_read_b128 v[114:117], v180 offset:1152
	v_pk_mul_f32 v[102:103], v[102:103], v[152:153] op_sel:[0,1]
	v_pk_mul_f32 v[104:105], v[104:105], v[152:153] op_sel:[0,1]
	v_pk_mul_f32 v[98:99], v[98:99], v[152:153] op_sel:[0,1]
	v_pk_mul_f32 v[100:101], v[100:101], v[152:153] op_sel:[0,1]
	v_cvt_pk_bf16_f32 v102, v102, v103
	v_cvt_pk_bf16_f32 v103, v104, v105
	v_cvt_pk_bf16_f32 v104, v98, v99
	v_cvt_pk_bf16_f32 v105, v100, v101
	v_pk_mul_f32 v[110:111], v[110:111], v[152:153] op_sel:[0,1]
	v_pk_mul_f32 v[112:113], v[112:113], v[152:153] op_sel:[0,1]
	v_pk_mul_f32 v[106:107], v[106:107], v[152:153] op_sel:[0,1]
	v_pk_mul_f32 v[108:109], v[108:109], v[152:153] op_sel:[0,1]
	s_waitcnt lgkmcnt(0)
	v_cvt_pk_bf16_f32 v110, v110, v111
	v_cvt_pk_bf16_f32 v111, v112, v113
	v_cvt_pk_bf16_f32 v112, v106, v107
	v_cvt_pk_bf16_f32 v113, v108, v109
	s_mov_b32 s100, s98
	s_mov_b32 s101, s99
	global_store_dwordx4 v200, v[122:125], s[100:101] nt
	s_add_u32 s100, s100, s67
	s_addc_u32 s101, s101, 0
	global_store_dwordx4 v200, v[114:117], s[100:101] nt
	ds_write_b128 v178, v[110:113]
	ds_write_b128 v178, v[102:105] offset:64
	ds_read_b128 v[106:109], v180
	ds_read_b128 v[98:101], v180 offset:1152
	v_pk_mul_f32 v[86:87], v[86:87], v[150:151] op_sel_hi:[1,0]
	v_pk_mul_f32 v[88:89], v[88:89], v[150:151] op_sel_hi:[1,0]
	v_pk_mul_f32 v[82:83], v[82:83], v[150:151] op_sel_hi:[1,0]
	v_pk_mul_f32 v[84:85], v[84:85], v[150:151] op_sel_hi:[1,0]
	v_cvt_pk_bf16_f32 v86, v86, v87
	v_cvt_pk_bf16_f32 v87, v88, v89
	v_cvt_pk_bf16_f32 v88, v82, v83
	v_cvt_pk_bf16_f32 v89, v84, v85
	v_pk_mul_f32 v[94:95], v[94:95], v[150:151] op_sel_hi:[1,0]
	v_pk_mul_f32 v[96:97], v[96:97], v[150:151] op_sel_hi:[1,0]
	v_pk_mul_f32 v[90:91], v[90:91], v[150:151] op_sel_hi:[1,0]
	v_pk_mul_f32 v[92:93], v[92:93], v[150:151] op_sel_hi:[1,0]
	s_waitcnt lgkmcnt(0)
	v_cvt_pk_bf16_f32 v94, v94, v95
	v_cvt_pk_bf16_f32 v95, v96, v97
	v_cvt_pk_bf16_f32 v96, v90, v91
	v_cvt_pk_bf16_f32 v97, v92, v93
	s_mul_i32 s44, s66, 16
	s_add_u32 s100, s98, s44
	s_addc_u32 s101, s99, 0
	global_store_dwordx4 v200, v[106:109], s[100:101] nt
	s_add_u32 s100, s100, s67
	s_addc_u32 s101, s101, 0
	global_store_dwordx4 v200, v[98:101], s[100:101] nt
	ds_write_b128 v178, v[94:97]
	ds_write_b128 v178, v[86:89] offset:64
	ds_read_b128 v[90:93], v180
	ds_read_b128 v[82:85], v180 offset:1152
	v_pk_mul_f32 v[70:71], v[70:71], v[150:151] op_sel:[0,1]
	v_pk_mul_f32 v[72:73], v[72:73], v[150:151] op_sel:[0,1]
	v_pk_mul_f32 v[66:67], v[66:67], v[150:151] op_sel:[0,1]
	v_pk_mul_f32 v[68:69], v[68:69], v[150:151] op_sel:[0,1]
	v_cvt_pk_bf16_f32 v70, v70, v71
	v_cvt_pk_bf16_f32 v71, v72, v73
	v_cvt_pk_bf16_f32 v72, v66, v67
	v_cvt_pk_bf16_f32 v73, v68, v69
	v_pk_mul_f32 v[78:79], v[78:79], v[150:151] op_sel:[0,1]
	v_pk_mul_f32 v[80:81], v[80:81], v[150:151] op_sel:[0,1]
	v_pk_mul_f32 v[74:75], v[74:75], v[150:151] op_sel:[0,1]
	v_pk_mul_f32 v[76:77], v[76:77], v[150:151] op_sel:[0,1]
	s_waitcnt lgkmcnt(0)
;     __device__ __forceinline__ void operator()(const f32x4 (&acc)[2][2][4][2], const Unit& u, int wr, int wc, int fr, int fq, PG8_LAS float* stash, int par, PG8_LAS unsigned char* stg, const Unit& un) const {
;     ...
;                     for (int i = 0; i < 4; ++i) { v[i] = acc[ai][bj][m][0][i] * rs; v[4 + i] = acc[ai][bj][m][1][i] * rs; }
;                     if (kind <= 1 && bj == 0) {
;                         const f32x4 c0 = *(const f32x4*)(cs + pos * 16), c1 = *(const f32x4*)(cs + pos * 16 + 4), s0 = *(const f32x4*)(cs + pos * 16 + 8), s1 = *(const f32x4*)(cs + pos * 16 + 12);
; #pragma unroll
;                         for (int i = 0; i < 8; ++i) {
;                             const float c = i < 4 ? c0[i & 3] : c1[i & 3], s = i < 4 ? s0[i & 3] : s1[i & 3];
;                             const float pr = peer_x16(v[i], fq);
;                             const float r = (fq == 0) ? (v[i] * c - pr * s) : (v[i] * c + pr * s);
;                             v[i] = (fq < 2) ? r : v[i];
;                         }
;                     }
;                     if (kind == 0) {
; #pragma unroll
;                         for (int i = 0; i < 8; ++i) v[i] *= C2Q;
;                     }
;                     { u32x4 w; w.x = cvt_pk_bf16(v[0], v[1]); w.y = cvt_pk_bf16(v[2], v[3]); w.z = cvt_pk_bf16(v[4], v[5]); w.w = cvt_pk_bf16(v[6], v[7]);
;                       *(PG8_LAS u32x4*)(stg + fr * 144 + fq * 16 + bj * 64) = w; }
;                 }
;                 {
;                     int kind;
;                     if (odd) kind = (u.pn < 6) ? 0 : (u.pn == 6 ? 1 : 2);
;                     else     kind = (u.pn < 2) ? 0 : (u.pn == 2 ? (wc < 2 ? 1 : 2) : 3);
; #pragma unroll
;                     for (int i = 0; i < 2; ++i) { const int c = fq * 16 + fr + 64 * i, rr = c >> 3, pc = c & 7;
;                         const u32x4 w = *(const PG8_LAS u32x4*)(stg + rr * 144 + pc * 16);
;                         const int rowc = row - fr + rr, posc = rowc & 4095;
;                         if (kind == 1 || kind == 2) {
;                             bf16_t* dst = (kind == 1) ? kd : vt;
;                             if (odd) *(u32x4*)(dst + (size_t)(b * 4 + wc) * (4096 * 64) + (size_t)((posc & 15) * 256 + (posc >> 4)) * 64 + pc * 8) = w;
;                             else     *(u32x4*)(dst + (size_t)(b * 2 + (wc & 1)) * (4096 * 64) + (size_t)posc * 64 + pc * 8) = w;
	v_cvt_pk_bf16_f32 v78, v78, v79
	v_cvt_pk_bf16_f32 v79, v80, v81
	v_cvt_pk_bf16_f32 v80, v74, v75
	v_cvt_pk_bf16_f32 v81, v76, v77
	s_mul_i32 s44, s66, 32
	s_add_u32 s100, s98, s44
	s_addc_u32 s101, s99, 0
	global_store_dwordx4 v200, v[90:93], s[100:101] nt
	s_add_u32 s100, s100, s67
	s_addc_u32 s101, s101, 0
	global_store_dwordx4 v200, v[82:85], s[100:101] nt
	ds_write_b128 v178, v[78:81]
	ds_write_b128 v178, v[70:73] offset:64
	ds_read_b128 v[74:77], v180
	ds_read_b128 v[66:69], v180 offset:1152
	v_pk_mul_f32 v[54:55], v[54:55], v[148:149] op_sel_hi:[1,0]
	v_pk_mul_f32 v[56:57], v[56:57], v[148:149] op_sel_hi:[1,0]
	v_pk_mul_f32 v[50:51], v[50:51], v[148:149] op_sel_hi:[1,0]
	v_pk_mul_f32 v[52:53], v[52:53], v[148:149] op_sel_hi:[1,0]
	v_cvt_pk_bf16_f32 v54, v54, v55
	v_cvt_pk_bf16_f32 v55, v56, v57
	v_cvt_pk_bf16_f32 v56, v50, v51
	v_cvt_pk_bf16_f32 v57, v52, v53
	v_pk_mul_f32 v[62:63], v[62:63], v[148:149] op_sel_hi:[1,0]
	v_pk_mul_f32 v[64:65], v[64:65], v[148:149] op_sel_hi:[1,0]
	v_pk_mul_f32 v[58:59], v[58:59], v[148:149] op_sel_hi:[1,0]
	v_pk_mul_f32 v[60:61], v[60:61], v[148:149] op_sel_hi:[1,0]
	s_waitcnt lgkmcnt(0)
	v_cvt_pk_bf16_f32 v62, v62, v63
	v_cvt_pk_bf16_f32 v63, v64, v65
	v_cvt_pk_bf16_f32 v64, v58, v59
	v_cvt_pk_bf16_f32 v65, v60, v61
	s_mul_i32 s44, s66, 48
	s_add_u32 s100, s98, s44
	s_addc_u32 s101, s99, 0
	global_store_dwordx4 v200, v[74:77], s[100:101] nt
	s_add_u32 s100, s100, s67
	s_addc_u32 s101, s101, 0
	global_store_dwordx4 v200, v[66:69], s[100:101] nt
	ds_write_b128 v178, v[62:65]
	ds_write_b128 v178, v[54:57] offset:64
	ds_read_b128 v[58:61], v180
	ds_read_b128 v[50:53], v180 offset:1152
	v_pk_mul_f32 v[38:39], v[38:39], v[148:149] op_sel:[0,1]
	v_pk_mul_f32 v[40:41], v[40:41], v[148:149] op_sel:[0,1]
	v_pk_mul_f32 v[34:35], v[34:35], v[148:149] op_sel:[0,1]
	v_pk_mul_f32 v[36:37], v[36:37], v[148:149] op_sel:[0,1]
	v_cvt_pk_bf16_f32 v38, v38, v39
	v_cvt_pk_bf16_f32 v39, v40, v41
	v_cvt_pk_bf16_f32 v40, v34, v35
	v_cvt_pk_bf16_f32 v41, v36, v37
	v_pk_mul_f32 v[46:47], v[46:47], v[148:149] op_sel:[0,1]
	v_pk_mul_f32 v[48:49], v[48:49], v[148:149] op_sel:[0,1]
	v_pk_mul_f32 v[42:43], v[42:43], v[148:149] op_sel:[0,1]
	v_pk_mul_f32 v[44:45], v[44:45], v[148:149] op_sel:[0,1]
	s_waitcnt lgkmcnt(0)
	v_cvt_pk_bf16_f32 v46, v46, v47
	v_cvt_pk_bf16_f32 v47, v48, v49
	v_cvt_pk_bf16_f32 v48, v42, v43
	v_cvt_pk_bf16_f32 v49, v44, v45
	s_mul_i32 s44, s66, 128
	s_add_u32 s100, s98, s44
	s_addc_u32 s101, s99, 0
	global_store_dwordx4 v200, v[58:61], s[100:101] nt
	s_add_u32 s100, s100, s67
	s_addc_u32 s101, s101, 0
	global_store_dwordx4 v200, v[50:53], s[100:101] nt
	ds_write_b128 v178, v[46:49]
	ds_write_b128 v178, v[38:41] offset:64
	ds_read_b128 v[42:45], v180
	ds_read_b128 v[34:37], v180 offset:1152
	v_pk_mul_f32 v[22:23], v[22:23], v[146:147] op_sel_hi:[1,0]
	v_pk_mul_f32 v[24:25], v[24:25], v[146:147] op_sel_hi:[1,0]
	v_pk_mul_f32 v[18:19], v[18:19], v[146:147] op_sel_hi:[1,0]
	v_pk_mul_f32 v[20:21], v[20:21], v[146:147] op_sel_hi:[1,0]
	v_cvt_pk_bf16_f32 v22, v22, v23
	v_cvt_pk_bf16_f32 v23, v24, v25
	v_cvt_pk_bf16_f32 v24, v18, v19
	v_cvt_pk_bf16_f32 v25, v20, v21
	v_pk_mul_f32 v[30:31], v[30:31], v[146:147] op_sel_hi:[1,0]
	v_pk_mul_f32 v[32:33], v[32:33], v[146:147] op_sel_hi:[1,0]
	v_pk_mul_f32 v[26:27], v[26:27], v[146:147] op_sel_hi:[1,0]
	v_pk_mul_f32 v[28:29], v[28:29], v[146:147] op_sel_hi:[1,0]
	s_waitcnt lgkmcnt(0)
	v_cvt_pk_bf16_f32 v30, v30, v31
	v_cvt_pk_bf16_f32 v31, v32, v33
	v_cvt_pk_bf16_f32 v32, v26, v27
	v_cvt_pk_bf16_f32 v33, v28, v29
	s_mul_i32 s44, s66, 144
	s_add_u32 s100, s98, s44
	s_addc_u32 s101, s99, 0
	global_store_dwordx4 v200, v[42:45], s[100:101] nt
	s_add_u32 s100, s100, s67
	s_addc_u32 s101, s101, 0
	global_store_dwordx4 v200, v[34:37], s[100:101] nt
	ds_write_b128 v178, v[30:33]
	ds_write_b128 v178, v[22:25] offset:64
	ds_read_b128 v[26:29], v180
	ds_read_b128 v[18:21], v180 offset:1152
	v_pk_mul_f32 v[6:7], v[6:7], v[146:147] op_sel:[0,1]
	v_pk_mul_f32 v[8:9], v[8:9], v[146:147] op_sel:[0,1]
	v_pk_mul_f32 v[2:3], v[2:3], v[146:147] op_sel:[0,1]
	v_pk_mul_f32 v[4:5], v[4:5], v[146:147] op_sel:[0,1]
	v_cvt_pk_bf16_f32 v6, v6, v7
	v_cvt_pk_bf16_f32 v7, v8, v9
	v_cvt_pk_bf16_f32 v8, v2, v3
	v_cvt_pk_bf16_f32 v9, v4, v5
	v_pk_mul_f32 v[14:15], v[14:15], v[146:147] op_sel:[0,1]
	v_pk_mul_f32 v[16:17], v[16:17], v[146:147] op_sel:[0,1]
	v_pk_mul_f32 v[10:11], v[10:11], v[146:147] op_sel:[0,1]
	v_pk_mul_f32 v[12:13], v[12:13], v[146:147] op_sel:[0,1]
	s_waitcnt lgkmcnt(0)
	v_cvt_pk_bf16_f32 v14, v14, v15
	v_cvt_pk_bf16_f32 v15, v16, v17
	v_cvt_pk_bf16_f32 v16, v10, v11
	v_cvt_pk_bf16_f32 v17, v12, v13
	s_mul_i32 s44, s66, 160
	s_add_u32 s100, s98, s44
	s_addc_u32 s101, s99, 0
	global_store_dwordx4 v200, v[26:29], s[100:101] nt
	s_add_u32 s100, s100, s67
	s_addc_u32 s101, s101, 0
	global_store_dwordx4 v200, v[18:21], s[100:101] nt
	ds_write_b128 v178, v[14:17]
	ds_write_b128 v178, v[6:9] offset:64
	ds_read_b128 v[10:13], v180
	ds_read_b128 v[2:5], v180 offset:1152
	s_waitcnt lgkmcnt(0)
	s_mul_i32 s44, s66, 176
	s_add_u32 s100, s98, s44
	s_addc_u32 s101, s99, 0
	global_store_dwordx4 v200, v[10:13], s[100:101] nt
	s_add_u32 s100, s100, s67
	s_addc_u32 s101, s101, 0
	global_store_dwordx4 v200, v[2:5], s[100:101] nt
; __device__ __forceinline__ float sum_x16(float s) { auto r = __builtin_amdgcn_permlane16_swap(__float_as_uint(s), __float_as_uint(s), false, false); return __uint_as_float(r[0]) + __uint_as_float(r[1]); }
; __device__ __forceinline__ float sum_x32(float s) { auto r = __builtin_amdgcn_permlane32_swap(__float_as_uint(s), __float_as_uint(s), false, false); return __uint_as_float(r[0]) + __uint_as_float(r[1]); }
; __device__ __forceinline__ void rows_part_reduce(const f32x4 (&pl)[2][4], float (&rs)[2][4]) {
; #pragma unroll
;     for (int ai = 0; ai < 2; ++ai)
; #pragma unroll
;         for (int m = 0; m < 4; ++m) { float s = (pl[ai][m][0] + pl[ai][m][1]) + (pl[ai][m][2] + pl[ai][m][3]); s = sum_x16(s); s = sum_x32(s); rs[ai][m] = __builtin_amdgcn_rsqf(s * (1.0f / 1024.0f) + 1e-6f); }
; }
;     __device__ __forceinline__ void operator()(const f32x4 (&acc)[2][2][4][2], const Unit& u, int wr, int wc, int fr, int fq, PG8_LAS float* stash, int par, PG8_LAS unsigned char* stg, const Unit& un) const {
;     ...
;         if (newpm) { float rsn[2][4]; rows_part_reduce(pln, rsn);
;           if (fq == 0) {
; #pragma unroll
;               for (int ai = 0; ai < 2; ++ai)
; #pragma unroll
;                   for (int m = 0; m < 4; ++m) stash[(par ^ 1) * 256 + ai * HALF + wr * 64 + m * 16 + fr] = rsn[ai][m]; } }
.Lipe_done:
	s_mov_b64 s[84:85], s[54:55]
	s_andn2_b64 vcc, exec, s[20:21]
	s_cbranch_vccnz .LBB0_353
	s_waitcnt vmcnt(0)
	v_add_f32_e32 v0, v207, v214
	v_add_f32_e32 v2, v216, v217
	v_add_f32_e32 v3, v198, v211
	v_add_f32_e32 v4, v213, v215
	v_add_f32_e32 v5, v195, v208
	v_add_f32_e32 v6, v210, v212
	v_add_f32_e32 v7, v192, v199
	v_add_f32_e32 v8, v206, v209
	v_add_f32_e32 v9, v189, v194
	v_add_f32_e32 v10, v197, v205
	v_add_f32_e32 v11, v185, v190
	v_add_f32_e32 v12, v193, v196
	v_add_f32_e32 v13, v183, v186
	v_add_f32_e32 v14, v188, v191
	v_add_f32_e32 v15, v181, v182
	v_add_f32_e32 v16, v184, v187
	v_add_f32_e32 v0, v0, v2
	v_add_f32_e32 v3, v3, v4
	v_add_f32_e32 v5, v5, v6
	v_add_f32_e32 v7, v7, v8
	v_add_f32_e32 v9, v9, v10
	v_add_f32_e32 v11, v11, v12
	v_add_f32_e32 v13, v13, v14
	v_add_f32_e32 v15, v15, v16
	v_mov_b32_e32 v2, v0
	v_mov_b32_e32 v4, v3
	v_mov_b32_e32 v6, v5
	v_mov_b32_e32 v8, v7
	v_mov_b32_e32 v10, v9
	v_mov_b32_e32 v12, v11
	v_mov_b32_e32 v14, v13
	v_mov_b32_e32 v16, v15
	v_permlane16_swap_b32_e32 v0, v2
	v_permlane16_swap_b32_e32 v3, v4
	v_permlane16_swap_b32_e32 v5, v6
	v_permlane16_swap_b32_e32 v7, v8
	v_permlane16_swap_b32_e32 v9, v10
	v_permlane16_swap_b32_e32 v11, v12
	v_permlane16_swap_b32_e32 v13, v14
	v_permlane16_swap_b32_e32 v15, v16
	v_add_f32_e32 v0, v0, v2
	v_add_f32_e32 v3, v3, v4
	v_add_f32_e32 v5, v5, v6
	v_add_f32_e32 v7, v7, v8
	v_add_f32_e32 v9, v9, v10
	v_add_f32_e32 v11, v11, v12
	v_add_f32_e32 v13, v13, v14
	v_add_f32_e32 v15, v15, v16
	v_mov_b32_e32 v2, v0
	v_mov_b32_e32 v4, v3
	v_mov_b32_e32 v6, v5
	v_mov_b32_e32 v8, v7
	v_mov_b32_e32 v10, v9
	v_mov_b32_e32 v12, v11
	v_mov_b32_e32 v14, v13
	v_mov_b32_e32 v16, v15
	v_permlane32_swap_b32_e32 v0, v2
	v_permlane32_swap_b32_e32 v3, v4
	v_permlane32_swap_b32_e32 v5, v6
	v_permlane32_swap_b32_e32 v7, v8
	v_permlane32_swap_b32_e32 v9, v10
	v_permlane32_swap_b32_e32 v11, v12
	v_permlane32_swap_b32_e32 v13, v14
	v_permlane32_swap_b32_e32 v15, v16
	s_and_saveexec_b64 s[18:19], s[34:35]
	s_cbranch_execz .LBB0_352
	v_add_f32_e32 v15, v15, v16
	v_mov_b32_e32 v16, 0x358637bd
	v_add_f32_e32 v3, v3, v4
	v_add_f32_e32 v0, v0, v2
	v_add_f32_e32 v7, v7, v8
	v_add_f32_e32 v5, v5, v6
	v_fmamk_f32 v3, v3, 0x3a800000, v16
	v_fmamk_f32 v0, v0, 0x3a800000, v16
	v_add_f32_e32 v11, v11, v12
	v_add_f32_e32 v9, v9, v10
	v_fmamk_f32 v7, v7, 0x3a800000, v16
	v_fmamk_f32 v5, v5, 0x3a800000, v16
	v_rsq_f32_e32 v3, v3
	v_rsq_f32_e32 v0, v0
	v_add_f32_e32 v13, v13, v14
	v_fmamk_f32 v11, v11, 0x3a800000, v16
	v_fmamk_f32 v9, v9, 0x3a800000, v16
	v_rsq_f32_e32 v7, v7
	v_rsq_f32_e32 v5, v5
	v_lshlrev_b32_e32 v2, 10, v179
	v_fmamk_f32 v15, v15, 0x3a800000, v16
	v_fmamk_f32 v13, v13, 0x3a800000, v16
	v_rsq_f32_e32 v11, v11
	v_rsq_f32_e32 v9, v9
	v_xor_b32_e32 v2, 0x400, v2
	v_rsq_f32_e32 v15, v15
	v_rsq_f32_e32 v13, v13
	v_add_u32_e32 v2, v172, v2
	ds_write2_b32 v2, v0, v3 offset1:16
	ds_write2_b32 v2, v5, v7 offset0:32 offset1:48
	ds_write2_b32 v2, v9, v11 offset0:128 offset1:144
	ds_write2_b32 v2, v13, v15 offset0:160 offset1:176
